# speedup vs baseline: 1.2184x; 1.0037x over previous
; DI float siluf(float z) { return z / (1.f + __expf(-z)); }
; DI void phase_gdn_prep(const Params& p, int bid, int nb, char* smem) {
;     ...
;       {
;         u32x4 z = (u32x4){0u, 0u, 0u, 0u};
;         const bool ok = !(n == 0 && rr == 0);
;         u32x4 a0 = ok ? *(const u32x4*)(p.gqkv + (size_t)(t0 + r0 - 3) * 1536 + gcol) : z;
;         u32x4 a1 = ok ? *(const u32x4*)(p.gqkv + (size_t)(t0 + r0 - 2) * 1536 + gcol) : z;
;         u32x4 a2 = ok ? *(const u32x4*)(p.gqkv + (size_t)(t0 + r0 - 1) * 1536 + gcol) : z;
;         unpack8(a0, w0); unpack8(a1, w1); unpack8(a2, w2);
;       }
; #pragma unroll
;       for (int i = 0; i < 16; i++) {
;         const int row = r0 + i;
;         float cur[8], o8[8];
;         unpack8(*(const u32x4*)(p.gqkv + (size_t)(t0 + row) * 1536 + gcol), cur);
;         float ss = 0.f;
; #pragma unroll
;         for (int e = 0; e < 8; e++) {
;           float v = cw[0][e] * w0[e] + cw[1][e] * w1[e] + cw[2][e] * w2[e] + cw[3][e] * cur[e];
;           v = siluf(v);
;           o8[e] = v; ss += v * v;
;           w0[e] = w1[e]; w1[e] = w2[e]; w2[e] = cur[e];
;         }
;         u32x4 pk = pack8(o8);
;         ss = sum16(ss);
;         if (tensor == 0) { *(u32x4*)(Qs + sw256(row, ch)) = pk; if (ch == 0) sSq[row] = ss; }
;         else if (tensor == 1) { *(u32x4*)(Ks + sw256(row, ch)) = pk; if (ch == 0) sSk[row] = ss; }
;         else { *(u32x4*)(Vs + row * 128 + ch * 8) = pk; }
;       }
.LBB0_193:
	s_or_b64 exec, exec, s[8:9]
	v_readlane_b32 s56, v253, 49
	v_readlane_b32 s62, v253, 55
	v_readlane_b32 s63, v253, 56
	s_waitcnt vmcnt(0)
	v_lshlrev_b32_e32 v70, 16, v38
	v_and_b32_e32 v71, 0xffff0000, v38
	v_lshlrev_b32_e32 v66, 16, v39
	v_and_b32_e32 v67, 0xffff0000, v39
	v_lshlrev_b32_e32 v58, 16, v40
	v_and_b32_e32 v59, 0xffff0000, v40
	v_add_u32_e32 v40, s77, v233
	v_mov_b64_e32 v[38:39], s[62:63]
	v_mad_i64_i32 v[38:39], s[38:39], v40, s81, v[38:39]
	v_lshl_add_u64 v[38:39], v[48:49], 1, v[38:39]
	v_lshlrev_b32_e32 v50, 16, v41
	v_and_b32_e32 v51, 0xffff0000, v41
	global_load_dwordx4 v[38:41], v[38:39], off
	v_lshlrev_b32_e32 v74, 16, v42
	v_and_b32_e32 v75, 0xffff0000, v42
	v_lshlrev_b32_e32 v72, 16, v43
	v_and_b32_e32 v73, 0xffff0000, v43
	v_lshlrev_b32_e32 v68, 16, v44
	v_and_b32_e32 v69, 0xffff0000, v44
	v_lshlrev_b32_e32 v60, 16, v45
	v_and_b32_e32 v61, 0xffff0000, v45
	v_cmp_ne_u32_e64 s[8:9], 1, v53
	v_lshlrev_b32_e32 v232, 1, v54
	v_cmp_lt_u32_e64 s[10:11], 15, v76
	v_cmp_eq_u32_e64 s[6:7], 0, v46
	v_readlane_b32 s57, v253, 50
	v_readlane_b32 s58, v253, 51
	v_readlane_b32 s59, v253, 52
	v_readlane_b32 s60, v253, 53
	v_readlane_b32 s61, v253, 54
	v_readlane_b32 s64, v253, 57
	v_readlane_b32 s65, v253, 58
	v_readlane_b32 s66, v253, 59
	v_readlane_b32 s67, v253, 60
	v_readlane_b32 s68, v253, 61
	v_readlane_b32 s69, v253, 62
	v_readlane_b32 s70, v253, 63
	v_readlane_b32 s71, v252, 0
	s_waitcnt vmcnt(0)
	v_lshlrev_b32_e32 v64, 16, v38
	v_and_b32_e32 v65, 0xffff0000, v38
	v_lshlrev_b32_e32 v56, 16, v39
	v_and_b32_e32 v57, 0xffff0000, v39
	v_lshlrev_b32_e32 v44, 16, v40
	v_and_b32_e32 v45, 0xffff0000, v40
	v_lshlrev_b32_e32 v42, 16, v41
	v_and_b32_e32 v43, 0xffff0000, v41
	v_lshlrev_b32_e32 v38, 16, v34
	v_and_b32_e32 v39, 0xffff0000, v34
	v_pk_mul_f32 v[40:41], v[30:31], v[74:75]
	s_nop 0
	v_pk_fma_f32 v[38:39], v[14:15], v[38:39], v[40:41]
	s_nop 0
	v_pk_fma_f32 v[38:39], v[18:19], v[70:71], v[38:39]
	s_nop 0
	v_pk_fma_f32 v[38:39], v[22:23], v[64:65], v[38:39]
	s_nop 0
	v_mul_f32_e32 v34, 0xbfb8aa3b, v38
	v_exp_f32_e32 v40, v34
	v_mul_f32_e32 v34, 0xbfb8aa3b, v39
	v_exp_f32_e32 v41, v34
	s_nop 0
	v_pk_add_f32 v[40:41], v[40:41], 1.0 op_sel_hi:[1,0]
	s_nop 0
	v_rcp_f32_e32 v53, v41
	s_nop 0
	v_mul_f32_e32 v41, v39, v53
	v_rcp_f32_e32 v39, v40
	s_nop 0
	v_mul_f32_e32 v40, v38, v39
	v_pk_mul_f32 v[38:39], v[40:41], v[40:41]
	v_cvt_pk_bf16_f32 v34, v40, v41
	v_lshlrev_b32_e32 v40, 16, v35
	v_and_b32_e32 v41, 0xffff0000, v35
	v_pk_mul_f32 v[54:55], v[32:33], v[72:73]
	s_nop 0
	v_pk_fma_f32 v[40:41], v[16:17], v[40:41], v[54:55]
	s_nop 0
	v_pk_fma_f32 v[40:41], v[20:21], v[66:67], v[40:41]
	s_nop 0
	v_pk_fma_f32 v[40:41], v[24:25], v[56:57], v[40:41]
	s_nop 0
	v_mul_f32_e32 v35, 0xbfb8aa3b, v40
	v_exp_f32_e32 v54, v35
	v_mul_f32_e32 v35, 0xbfb8aa3b, v41
	v_exp_f32_e32 v55, v35
	s_nop 0
	v_pk_add_f32 v[54:55], v[54:55], 1.0 op_sel_hi:[1,0]
	s_nop 0
	v_rcp_f32_e32 v53, v55
	s_nop 0
	v_mul_f32_e32 v41, v41, v53
	v_rcp_f32_e32 v53, v54
	s_nop 0
	v_mul_f32_e32 v40, v40, v53
	v_pk_mul_f32 v[54:55], v[40:41], v[40:41]
	v_cvt_pk_bf16_f32 v35, v40, v41
	v_lshlrev_b32_e32 v40, 16, v36
	v_and_b32_e32 v41, 0xffff0000, v36
	v_pk_mul_f32 v[62:63], v[26:27], v[68:69]
	s_nop 0
	v_pk_fma_f32 v[40:41], v[2:3], v[40:41], v[62:63]
	s_nop 0
	v_pk_fma_f32 v[40:41], v[6:7], v[58:59], v[40:41]
	s_nop 0
	v_pk_fma_f32 v[40:41], v[10:11], v[44:45], v[40:41]
	s_nop 0
	v_mul_f32_e32 v36, 0xbfb8aa3b, v40
	v_exp_f32_e32 v62, v36
	v_mul_f32_e32 v36, 0xbfb8aa3b, v41
	v_exp_f32_e32 v63, v36
	s_nop 0
	v_pk_add_f32 v[62:63], v[62:63], 1.0 op_sel_hi:[1,0]
	s_nop 0
	v_rcp_f32_e32 v53, v63
	s_nop 0
	v_mul_f32_e32 v41, v41, v53
	v_rcp_f32_e32 v53, v62
	s_nop 0
	v_mul_f32_e32 v40, v40, v53
	v_pk_mul_f32 v[62:63], v[40:41], v[40:41]
	v_cvt_pk_bf16_f32 v36, v40, v41
	v_lshlrev_b32_e32 v40, 16, v37
	v_and_b32_e32 v41, 0xffff0000, v37
	v_pk_mul_f32 v[234:235], v[28:29], v[60:61]
	s_nop 0
	v_pk_fma_f32 v[40:41], v[4:5], v[40:41], v[234:235]
	s_nop 0
	v_pk_fma_f32 v[40:41], v[8:9], v[50:51], v[40:41]
	s_nop 0
	v_pk_fma_f32 v[40:41], v[12:13], v[42:43], v[40:41]
	s_nop 0
	v_mul_f32_e32 v37, 0xbfb8aa3b, v40
	v_exp_f32_e32 v234, v37
	v_mul_f32_e32 v37, 0xbfb8aa3b, v41
	v_exp_f32_e32 v235, v37
	s_nop 0
	v_pk_add_f32 v[234:235], v[234:235], 1.0 op_sel_hi:[1,0]
	s_nop 0
	v_rcp_f32_e32 v53, v235
	s_nop 0
	v_mul_f32_e32 v41, v41, v53
	v_rcp_f32_e32 v53, v234
	s_nop 0
	v_mul_f32_e32 v40, v40, v53
	v_add_f32_e32 v37, v38, v39
	v_add_f32_e32 v37, v54, v37
	v_add_f32_e32 v37, v55, v37
	v_add_f32_e32 v37, v62, v37
	v_pk_mul_f32 v[234:235], v[40:41], v[40:41]
	v_add_f32_e32 v37, v63, v37
	v_add_f32_e32 v37, v234, v37
	v_add_f32_e32 v38, v235, v37
	v_cvt_pk_bf16_f32 v37, v40, v41
	v_lshlrev_b32_e32 v39, 12, v52
	v_add_f32_dpp v38, v38, v38 quad_perm:[1,0,3,2] row_mask:0xf bank_mask:0xf bound_ctrl:1
	s_nop 1
	v_add_f32_dpp v38, v38, v38 quad_perm:[2,3,0,1] row_mask:0xf bank_mask:0xf bound_ctrl:1
	s_nop 1
	v_add_f32_dpp v38, v38, v38 row_half_mirror row_mask:0xf bank_mask:0xf bound_ctrl:1
	s_nop 1
	v_add_f32_dpp v38, v38, v38 row_mirror row_mask:0xf bank_mask:0xf bound_ctrl:1
	s_and_saveexec_b64 s[38:39], s[10:11]
	s_xor_b64 s[38:39], exec, s[38:39]
	s_cbranch_execz .LBB0_201
	s_and_saveexec_b64 s[46:47], s[8:9]
	s_xor_b64 s[46:47], exec, s[46:47]
	v_add_u32_e32 v38, v232, v39
	ds_write_b128 v38, v[34:37] offset:33024
	s_andn2_saveexec_b64 s[46:47], s[46:47]
	s_cbranch_execz .LBB0_200
	v_lshl_add_u32 v39, v46, 4, v39
	ds_write_b128 v39, v[34:37] offset:16640
	s_and_saveexec_b64 s[48:49], s[6:7]
	v_lshl_add_u32 v34, v233, 2, v224
	ds_write_b32 v34, v38
	s_or_b64 exec, exec, s[48:49]

; DI float siluf(float z) { return z / (1.f + __expf(-z)); }
; DI void phase_gdn_prep(const Params& p, int bid, int nb, char* smem) {
;     ...
; #pragma unroll
;       for (int i = 0; i < 16; i++) {
;         const int row = r0 + i;
;         float cur[8], o8[8];
;         unpack8(*(const u32x4*)(p.gqkv + (size_t)(t0 + row) * 1536 + gcol), cur);
;         float ss = 0.f;
; #pragma unroll
;         for (int e = 0; e < 8; e++) {
;           float v = cw[0][e] * w0[e] + cw[1][e] * w1[e] + cw[2][e] * w2[e] + cw[3][e] * cur[e];
;           v = siluf(v);
;           o8[e] = v; ss += v * v;
;           w0[e] = w1[e]; w1[e] = w2[e]; w2[e] = cur[e];
;         }
;         u32x4 pk = pack8(o8);
;         ss = sum16(ss);
;         if (tensor == 0) { *(u32x4*)(Qs + sw256(row, ch)) = pk; if (ch == 0) sSq[row] = ss; }
;         else if (tensor == 1) { *(u32x4*)(Ks + sw256(row, ch)) = pk; if (ch == 0) sSk[row] = ss; }
;         else { *(u32x4*)(Vs + row * 128 + ch * 8) = pk; }
;       }
.LBB0_205:
	s_or_b64 exec, exec, s[38:39]
	v_readlane_b32 s56, v253, 49
	v_or_b32_e32 v77, 1, v233
	v_readlane_b32 s62, v253, 55
	v_readlane_b32 s63, v253, 56
	v_add_u32_e32 v36, s77, v77
	v_readlane_b32 s57, v253, 50
	v_mov_b64_e32 v[34:35], s[62:63]
	v_mad_i64_i32 v[34:35], s[38:39], v36, s81, v[34:35]
	v_lshl_add_u64 v[34:35], v[48:49], 1, v[34:35]
	global_load_dwordx4 v[34:37], v[34:35], off
	v_readlane_b32 s58, v253, 51
	v_readlane_b32 s59, v253, 52
	v_readlane_b32 s60, v253, 53
	v_readlane_b32 s61, v253, 54
	v_readlane_b32 s64, v253, 57
	v_readlane_b32 s65, v253, 58
	v_readlane_b32 s66, v253, 59
	v_readlane_b32 s67, v253, 60
	v_readlane_b32 s68, v253, 61
	v_readlane_b32 s69, v253, 62
	v_readlane_b32 s70, v253, 63
	v_readlane_b32 s71, v252, 0
	s_waitcnt vmcnt(0)
	v_lshlrev_b32_e32 v62, 16, v34
	v_and_b32_e32 v63, 0xffff0000, v34
	v_lshlrev_b32_e32 v54, 16, v35
	v_and_b32_e32 v55, 0xffff0000, v35
	v_pk_mul_f32 v[34:35], v[30:31], v[70:71]
	v_lshlrev_b32_e32 v52, 16, v36
	v_pk_fma_f32 v[34:35], v[14:15], v[74:75], v[34:35]
	v_and_b32_e32 v53, 0xffff0000, v36
	v_pk_fma_f32 v[34:35], v[18:19], v[64:65], v[34:35]
	v_lshlrev_b32_e32 v38, 16, v37
	v_pk_fma_f32 v[34:35], v[22:23], v[62:63], v[34:35]
	v_and_b32_e32 v39, 0xffff0000, v37
	v_mul_f32_e32 v36, 0xbfb8aa3b, v34
	v_mul_f32_e32 v37, 0xbfb8aa3b, v35
	v_exp_f32_e32 v36, v36
	v_exp_f32_e32 v37, v37
	s_nop 0
	v_pk_add_f32 v[36:37], v[36:37], 1.0 op_sel_hi:[1,0]
	s_nop 0
	v_rcp_f32_e32 v41, v37
	s_nop 0
	v_mul_f32_e32 v35, v35, v41
	v_rcp_f32_e32 v40, v36
	s_nop 0
	v_mul_f32_e32 v34, v34, v40
	v_pk_mul_f32 v[36:37], v[32:33], v[66:67]
	v_pk_mul_f32 v[40:41], v[34:35], v[34:35]
	v_pk_fma_f32 v[36:37], v[16:17], v[72:73], v[36:37]
	v_cvt_pk_bf16_f32 v34, v34, v35
	v_pk_fma_f32 v[36:37], v[20:21], v[56:57], v[36:37]
	s_nop 0
	v_pk_fma_f32 v[36:37], v[24:25], v[54:55], v[36:37]
	s_nop 0
	v_mul_f32_e32 v35, 0xbfb8aa3b, v36
	v_exp_f32_e32 v72, v35
	v_mul_f32_e32 v35, 0xbfb8aa3b, v37
	v_exp_f32_e32 v73, v35
	s_nop 0
	v_pk_add_f32 v[72:73], v[72:73], 1.0 op_sel_hi:[1,0]
	s_nop 0
	v_rcp_f32_e32 v74, v73
	s_nop 0
	v_mul_f32_e32 v37, v37, v74
	v_rcp_f32_e32 v73, v72
	s_nop 0
	v_mul_f32_e32 v36, v36, v73
	v_pk_mul_f32 v[72:73], v[36:37], v[36:37]
	v_cvt_pk_bf16_f32 v35, v36, v37
	v_pk_mul_f32 v[36:37], v[26:27], v[58:59]
	s_nop 0
	v_pk_fma_f32 v[36:37], v[2:3], v[68:69], v[36:37]
	s_nop 0
	v_pk_fma_f32 v[36:37], v[6:7], v[44:45], v[36:37]
	s_nop 0
	v_pk_fma_f32 v[36:37], v[10:11], v[52:53], v[36:37]
	s_nop 0
	v_mul_f32_e32 v68, 0xbfb8aa3b, v36
	v_mul_f32_e32 v69, 0xbfb8aa3b, v37
	v_exp_f32_e32 v68, v68
	v_exp_f32_e32 v69, v69
	s_nop 0
	v_pk_add_f32 v[68:69], v[68:69], 1.0 op_sel_hi:[1,0]
	s_nop 0
	v_rcp_f32_e32 v75, v69
	s_nop 0
	v_mul_f32_e32 v37, v37, v75
	v_div_scale_f32 v69, s[38:39], v68, v68, v36
	v_rcp_f32_e32 v74, v69
	s_nop 0
	v_fma_f32 v75, -v69, v74, 1.0
	v_fmac_f32_e32 v74, v75, v74
	v_div_scale_f32 v75, vcc, v36, v68, v36
	v_mul_f32_e32 v234, v75, v74
	v_fma_f32 v235, -v69, v234, v75
	v_fmac_f32_e32 v234, v235, v74
	v_fma_f32 v69, -v69, v234, v75
	v_div_fmas_f32 v69, v69, v74, v234
	v_pk_mul_f32 v[74:75], v[28:29], v[50:51]
	v_div_fixup_f32 v36, v69, v68, v36
	v_pk_fma_f32 v[60:61], v[4:5], v[60:61], v[74:75]
	v_pk_mul_f32 v[68:69], v[36:37], v[36:37]
	v_pk_fma_f32 v[60:61], v[8:9], v[42:43], v[60:61]
	v_cvt_pk_bf16_f32 v36, v36, v37
	v_pk_fma_f32 v[60:61], v[12:13], v[38:39], v[60:61]
	s_nop 0
	v_mul_f32_e32 v37, 0xbfb8aa3b, v60
	v_exp_f32_e32 v74, v37
	v_mul_f32_e32 v37, 0xbfb8aa3b, v61
	v_exp_f32_e32 v75, v37
	s_nop 0
	v_pk_add_f32 v[74:75], v[74:75], 1.0 op_sel_hi:[1,0]
	s_nop 0
	v_rcp_f32_e32 v234, v75
	s_nop 0
	v_mul_f32_e32 v61, v61, v234
	v_rcp_f32_e32 v75, v74
	s_nop 0
	v_mul_f32_e32 v60, v60, v75
	v_add_f32_e32 v37, v40, v41
	v_add_f32_e32 v37, v72, v37
	v_add_f32_e32 v37, v73, v37
	v_add_f32_e32 v37, v68, v37
	v_pk_mul_f32 v[74:75], v[60:61], v[60:61]
	v_add_f32_e32 v37, v69, v37
	v_add_f32_e32 v37, v74, v37
	v_add_f32_e32 v40, v75, v37
	v_cvt_pk_bf16_f32 v37, v60, v61
	v_lshlrev_b32_e32 v41, 8, v77
	v_add_f32_dpp v40, v40, v40 quad_perm:[1,0,3,2] row_mask:0xf bank_mask:0xf bound_ctrl:1
	s_nop 1
	v_add_f32_dpp v40, v40, v40 quad_perm:[2,3,0,1] row_mask:0xf bank_mask:0xf bound_ctrl:1
	s_nop 1
	v_add_f32_dpp v40, v40, v40 row_half_mirror row_mask:0xf bank_mask:0xf bound_ctrl:1
	s_nop 1
	v_add_f32_dpp v40, v40, v40 row_mirror row_mask:0xf bank_mask:0xf bound_ctrl:1
	s_and_saveexec_b64 s[38:39], s[10:11]
	s_xor_b64 s[38:39], exec, s[38:39]
	s_cbranch_execz .LBB0_213
	s_and_saveexec_b64 s[46:47], s[8:9]
	s_xor_b64 s[46:47], exec, s[46:47]
	v_add_u32_e32 v40, v232, v41
	ds_write_b128 v40, v[34:37] offset:33024
	s_andn2_saveexec_b64 s[46:47], s[46:47]
	s_cbranch_execz .LBB0_212
	v_lshlrev_b32_e32 v60, 4, v46
	v_xad_u32 v41, v60, 16, v41
	ds_write_b128 v41, v[34:37] offset:16640
	s_and_saveexec_b64 s[48:49], s[6:7]
	v_lshl_add_u32 v34, v77, 2, v224
	ds_write_b32 v34, v40
	s_or_b64 exec, exec, s[48:49]

; DI float siluf(float z) { return z / (1.f + __expf(-z)); }
; DI void phase_gdn_prep(const Params& p, int bid, int nb, char* smem) {
;     ...
; #pragma unroll
;       for (int i = 0; i < 16; i++) {
;         const int row = r0 + i;
;         float cur[8], o8[8];
;         unpack8(*(const u32x4*)(p.gqkv + (size_t)(t0 + row) * 1536 + gcol), cur);
;         float ss = 0.f;
; #pragma unroll
;         for (int e = 0; e < 8; e++) {
;           float v = cw[0][e] * w0[e] + cw[1][e] * w1[e] + cw[2][e] * w2[e] + cw[3][e] * cur[e];
;           v = siluf(v);
;           o8[e] = v; ss += v * v;
;           w0[e] = w1[e]; w1[e] = w2[e]; w2[e] = cur[e];
;         }
;         u32x4 pk = pack8(o8);
;         ss = sum16(ss);
;         if (tensor == 0) { *(u32x4*)(Qs + sw256(row, ch)) = pk; if (ch == 0) sSq[row] = ss; }
;         else if (tensor == 1) { *(u32x4*)(Ks + sw256(row, ch)) = pk; if (ch == 0) sSk[row] = ss; }
;         else { *(u32x4*)(Vs + row * 128 + ch * 8) = pk; }
;       }
.LBB0_217:
	s_or_b64 exec, exec, s[38:39]
	v_readlane_b32 s56, v253, 49
	v_or_b32_e32 v72, 2, v233
	v_readlane_b32 s62, v253, 55
	v_readlane_b32 s63, v253, 56
	v_add_u32_e32 v36, s77, v72
	v_readlane_b32 s57, v253, 50
	v_mov_b64_e32 v[34:35], s[62:63]
	v_mad_i64_i32 v[34:35], s[38:39], v36, s81, v[34:35]
	v_lshl_add_u64 v[34:35], v[48:49], 1, v[34:35]
	global_load_dwordx4 v[34:37], v[34:35], off
	v_readlane_b32 s58, v253, 51
	v_readlane_b32 s59, v253, 52
	v_readlane_b32 s60, v253, 53
	v_readlane_b32 s61, v253, 54
	v_readlane_b32 s64, v253, 57
	v_readlane_b32 s65, v253, 58
	v_readlane_b32 s66, v253, 59
	v_readlane_b32 s67, v253, 60
	v_readlane_b32 s68, v253, 61
	v_readlane_b32 s69, v253, 62
	v_readlane_b32 s70, v253, 63
	v_readlane_b32 s71, v252, 0
	s_waitcnt vmcnt(0)
	v_lshlrev_b32_e32 v76, 16, v34
	v_and_b32_e32 v77, 0xffff0000, v34
	v_lshlrev_b32_e32 v68, 16, v35
	v_and_b32_e32 v69, 0xffff0000, v35
	v_pk_mul_f32 v[34:35], v[30:31], v[64:65]
	v_lshlrev_b32_e32 v60, 16, v36
	v_pk_fma_f32 v[34:35], v[14:15], v[70:71], v[34:35]
	v_and_b32_e32 v61, 0xffff0000, v36
	v_pk_fma_f32 v[34:35], v[18:19], v[62:63], v[34:35]
	v_lshlrev_b32_e32 v40, 16, v37
	v_pk_fma_f32 v[34:35], v[22:23], v[76:77], v[34:35]
	v_and_b32_e32 v41, 0xffff0000, v37
	v_mul_f32_e32 v36, 0xbfb8aa3b, v34
	v_mul_f32_e32 v37, 0xbfb8aa3b, v35
	v_exp_f32_e32 v36, v36
	v_exp_f32_e32 v37, v37
	s_nop 0
	v_pk_add_f32 v[36:37], v[36:37], 1.0 op_sel_hi:[1,0]
	s_nop 0
	v_rcp_f32_e32 v71, v37
	s_nop 0
	v_mul_f32_e32 v35, v35, v71
	v_rcp_f32_e32 v70, v36
	s_nop 0
	v_mul_f32_e32 v34, v34, v70
	v_pk_mul_f32 v[36:37], v[32:33], v[56:57]
	v_pk_mul_f32 v[70:71], v[34:35], v[34:35]
	v_pk_fma_f32 v[36:37], v[16:17], v[66:67], v[36:37]
	v_cvt_pk_bf16_f32 v34, v34, v35
	v_pk_fma_f32 v[36:37], v[20:21], v[54:55], v[36:37]
	s_nop 0
	v_pk_fma_f32 v[36:37], v[24:25], v[68:69], v[36:37]
	s_nop 0
	v_mul_f32_e32 v35, 0xbfb8aa3b, v36
	v_exp_f32_e32 v66, v35
	v_mul_f32_e32 v35, 0xbfb8aa3b, v37
	v_exp_f32_e32 v67, v35
	s_nop 0
	v_pk_add_f32 v[66:67], v[66:67], 1.0 op_sel_hi:[1,0]
	s_nop 0
	v_rcp_f32_e32 v73, v67
	s_nop 0
	v_mul_f32_e32 v37, v37, v73
	v_rcp_f32_e32 v67, v66
	s_nop 0
	v_mul_f32_e32 v36, v36, v67
	v_pk_mul_f32 v[66:67], v[36:37], v[36:37]
	v_cvt_pk_bf16_f32 v35, v36, v37
	v_pk_mul_f32 v[36:37], v[26:27], v[44:45]
	s_nop 0
	v_pk_fma_f32 v[36:37], v[2:3], v[58:59], v[36:37]
	s_nop 0
	v_pk_fma_f32 v[36:37], v[6:7], v[52:53], v[36:37]
	s_nop 0
	v_pk_fma_f32 v[36:37], v[10:11], v[60:61], v[36:37]
	s_nop 0
	v_mul_f32_e32 v58, 0xbfb8aa3b, v36
	v_mul_f32_e32 v59, 0xbfb8aa3b, v37
	v_exp_f32_e32 v58, v58
	v_exp_f32_e32 v59, v59
	s_nop 0
	v_pk_add_f32 v[58:59], v[58:59], 1.0 op_sel_hi:[1,0]
	s_nop 0
	v_rcp_f32_e32 v74, v59
	s_nop 0
	v_mul_f32_e32 v37, v37, v74
	v_div_scale_f32 v59, s[38:39], v58, v58, v36
	v_rcp_f32_e32 v73, v59
	s_nop 0
	v_fma_f32 v74, -v59, v73, 1.0
	v_fmac_f32_e32 v73, v74, v73
	v_div_scale_f32 v74, vcc, v36, v58, v36
	v_mul_f32_e32 v75, v74, v73
	v_fma_f32 v235, -v59, v75, v74
	v_fmac_f32_e32 v75, v235, v73
	v_fma_f32 v59, -v59, v75, v74
	v_div_fmas_f32 v59, v59, v73, v75
	v_pk_mul_f32 v[74:75], v[28:29], v[42:43]
	v_div_fixup_f32 v36, v59, v58, v36
	v_pk_fma_f32 v[50:51], v[4:5], v[50:51], v[74:75]
	v_pk_mul_f32 v[58:59], v[36:37], v[36:37]
	v_pk_fma_f32 v[50:51], v[8:9], v[38:39], v[50:51]
	v_cvt_pk_bf16_f32 v36, v36, v37
	v_pk_fma_f32 v[50:51], v[12:13], v[40:41], v[50:51]
	s_nop 0
	v_mul_f32_e32 v37, 0xbfb8aa3b, v50
	v_exp_f32_e32 v74, v37
	v_mul_f32_e32 v37, 0xbfb8aa3b, v51
	v_exp_f32_e32 v75, v37
	s_nop 0
	v_pk_add_f32 v[74:75], v[74:75], 1.0 op_sel_hi:[1,0]
	s_nop 0
	v_rcp_f32_e32 v73, v75
	s_nop 0
	v_mul_f32_e32 v51, v51, v73
	v_rcp_f32_e32 v73, v74
	s_nop 0
	v_mul_f32_e32 v50, v50, v73
	v_add_f32_e32 v37, v70, v71
	v_add_f32_e32 v37, v66, v37
	v_add_f32_e32 v37, v67, v37
	v_add_f32_e32 v37, v58, v37
	v_pk_mul_f32 v[74:75], v[50:51], v[50:51]
	v_add_f32_e32 v37, v59, v37
	v_add_f32_e32 v37, v74, v37
	v_add_f32_e32 v58, v75, v37
	v_cvt_pk_bf16_f32 v37, v50, v51
	v_lshlrev_b32_e32 v51, 8, v72
	v_add_f32_dpp v50, v58, v58 quad_perm:[1,0,3,2] row_mask:0xf bank_mask:0xf bound_ctrl:1
	s_nop 1
	v_add_f32_dpp v50, v50, v50 quad_perm:[2,3,0,1] row_mask:0xf bank_mask:0xf bound_ctrl:1
	s_nop 1
	v_add_f32_dpp v50, v50, v50 row_half_mirror row_mask:0xf bank_mask:0xf bound_ctrl:1
	s_nop 1
	v_add_f32_dpp v50, v50, v50 row_mirror row_mask:0xf bank_mask:0xf bound_ctrl:1
	s_and_saveexec_b64 s[38:39], s[10:11]
	s_xor_b64 s[38:39], exec, s[38:39]
	s_cbranch_execz .LBB0_225
	s_and_saveexec_b64 s[46:47], s[8:9]
	s_xor_b64 s[46:47], exec, s[46:47]
	v_add_u32_e32 v50, v232, v51
	ds_write_b128 v50, v[34:37] offset:33024
	s_andn2_saveexec_b64 s[46:47], s[46:47]
	s_cbranch_execz .LBB0_224
	v_lshlrev_b32_e32 v58, 4, v46
	v_xad_u32 v51, v58, 32, v51
	ds_write_b128 v51, v[34:37] offset:16640
	s_and_saveexec_b64 s[48:49], s[6:7]
	v_lshl_add_u32 v34, v72, 2, v224
	ds_write_b32 v34, v50
	s_or_b64 exec, exec, s[48:49]

; DI float siluf(float z) { return z / (1.f + __expf(-z)); }
; DI void phase_gdn_prep(const Params& p, int bid, int nb, char* smem) {
;     ...
; #pragma unroll
;       for (int i = 0; i < 16; i++) {
;         const int row = r0 + i;
;         float cur[8], o8[8];
;         unpack8(*(const u32x4*)(p.gqkv + (size_t)(t0 + row) * 1536 + gcol), cur);
;         float ss = 0.f;
; #pragma unroll
;         for (int e = 0; e < 8; e++) {
;           float v = cw[0][e] * w0[e] + cw[1][e] * w1[e] + cw[2][e] * w2[e] + cw[3][e] * cur[e];
;           v = siluf(v);
;           o8[e] = v; ss += v * v;
;           w0[e] = w1[e]; w1[e] = w2[e]; w2[e] = cur[e];
;         }
;         u32x4 pk = pack8(o8);
;         ss = sum16(ss);
;         if (tensor == 0) { *(u32x4*)(Qs + sw256(row, ch)) = pk; if (ch == 0) sSq[row] = ss; }
;         else if (tensor == 1) { *(u32x4*)(Ks + sw256(row, ch)) = pk; if (ch == 0) sSk[row] = ss; }
;         else { *(u32x4*)(Vs + row * 128 + ch * 8) = pk; }
;       }
.LBB0_229:
	s_or_b64 exec, exec, s[38:39]
	v_readlane_b32 s56, v253, 49
	v_or_b32_e32 v70, 3, v233
	v_readlane_b32 s62, v253, 55
	v_readlane_b32 s63, v253, 56
	v_add_u32_e32 v36, s77, v70
	v_readlane_b32 s57, v253, 50
	v_mov_b64_e32 v[34:35], s[62:63]
	v_mad_i64_i32 v[34:35], s[38:39], v36, s81, v[34:35]
	v_lshl_add_u64 v[34:35], v[48:49], 1, v[34:35]
	global_load_dwordx4 v[34:37], v[34:35], off
	v_readlane_b32 s58, v253, 51
	v_readlane_b32 s59, v253, 52
	v_readlane_b32 s60, v253, 53
	v_readlane_b32 s61, v253, 54
	v_readlane_b32 s64, v253, 57
	v_readlane_b32 s65, v253, 58
	v_readlane_b32 s66, v253, 59
	v_readlane_b32 s67, v253, 60
	v_readlane_b32 s68, v253, 61
	v_readlane_b32 s69, v253, 62
	v_readlane_b32 s70, v253, 63
	v_readlane_b32 s71, v252, 0
	s_waitcnt vmcnt(0)
	v_lshlrev_b32_e32 v74, 16, v34
	v_and_b32_e32 v75, 0xffff0000, v34
	v_lshlrev_b32_e32 v66, 16, v35
	v_and_b32_e32 v67, 0xffff0000, v35
	v_pk_mul_f32 v[34:35], v[30:31], v[62:63]
	v_lshlrev_b32_e32 v58, 16, v36
	v_pk_fma_f32 v[34:35], v[14:15], v[64:65], v[34:35]
	v_and_b32_e32 v59, 0xffff0000, v36
	v_pk_fma_f32 v[34:35], v[18:19], v[76:77], v[34:35]
	v_lshlrev_b32_e32 v50, 16, v37
	v_pk_fma_f32 v[34:35], v[22:23], v[74:75], v[34:35]
	v_and_b32_e32 v51, 0xffff0000, v37
	v_mul_f32_e32 v36, 0xbfb8aa3b, v34
	v_mul_f32_e32 v37, 0xbfb8aa3b, v35
	v_exp_f32_e32 v36, v36
	v_exp_f32_e32 v37, v37
	s_nop 0
	v_pk_add_f32 v[36:37], v[36:37], 1.0 op_sel_hi:[1,0]
	s_nop 0
	v_rcp_f32_e32 v65, v37
	s_nop 0
	v_mul_f32_e32 v35, v35, v65
	v_rcp_f32_e32 v64, v36
	s_nop 0
	v_mul_f32_e32 v34, v34, v64
	v_pk_mul_f32 v[36:37], v[32:33], v[54:55]
	v_pk_mul_f32 v[64:65], v[34:35], v[34:35]
	v_pk_fma_f32 v[36:37], v[16:17], v[56:57], v[36:37]
	v_cvt_pk_bf16_f32 v34, v34, v35
	v_pk_fma_f32 v[36:37], v[20:21], v[68:69], v[36:37]
	s_nop 0
	v_pk_fma_f32 v[36:37], v[24:25], v[66:67], v[36:37]
	s_nop 0
	v_mul_f32_e32 v35, 0xbfb8aa3b, v36
	v_exp_f32_e32 v56, v35
	v_mul_f32_e32 v35, 0xbfb8aa3b, v37
	v_exp_f32_e32 v57, v35
	s_nop 0
	v_pk_add_f32 v[56:57], v[56:57], 1.0 op_sel_hi:[1,0]
	s_nop 0
	v_rcp_f32_e32 v71, v57
	s_nop 0
	v_mul_f32_e32 v37, v37, v71
	v_rcp_f32_e32 v57, v56
	s_nop 0
	v_mul_f32_e32 v36, v36, v57
	v_pk_mul_f32 v[56:57], v[36:37], v[36:37]
	v_cvt_pk_bf16_f32 v35, v36, v37
	v_pk_mul_f32 v[36:37], v[26:27], v[52:53]
	s_nop 0
	v_pk_fma_f32 v[36:37], v[2:3], v[44:45], v[36:37]
	s_nop 0
	v_pk_fma_f32 v[36:37], v[6:7], v[60:61], v[36:37]
	s_nop 0
	v_pk_fma_f32 v[36:37], v[10:11], v[58:59], v[36:37]
	s_nop 0
	v_mul_f32_e32 v44, 0xbfb8aa3b, v36
	v_mul_f32_e32 v45, 0xbfb8aa3b, v37
	v_exp_f32_e32 v44, v44
	v_exp_f32_e32 v45, v45
	s_nop 0
	v_pk_add_f32 v[44:45], v[44:45], 1.0 op_sel_hi:[1,0]
	s_nop 0
	v_rcp_f32_e32 v72, v45
	s_nop 0
	v_mul_f32_e32 v37, v37, v72
	v_div_scale_f32 v45, s[38:39], v44, v44, v36
	v_rcp_f32_e32 v71, v45
	s_nop 0
	v_fma_f32 v72, -v45, v71, 1.0
	v_fmac_f32_e32 v71, v72, v71
	v_div_scale_f32 v72, vcc, v36, v44, v36
	v_mul_f32_e32 v73, v72, v71
	v_fma_f32 v235, -v45, v73, v72
	v_fmac_f32_e32 v73, v235, v71
	v_fma_f32 v45, -v45, v73, v72
	v_div_fmas_f32 v45, v45, v71, v73
	v_pk_mul_f32 v[72:73], v[28:29], v[38:39]
	v_div_fixup_f32 v36, v45, v44, v36
	v_pk_fma_f32 v[42:43], v[4:5], v[42:43], v[72:73]
	v_pk_mul_f32 v[44:45], v[36:37], v[36:37]
	v_pk_fma_f32 v[42:43], v[8:9], v[40:41], v[42:43]
	v_cvt_pk_bf16_f32 v36, v36, v37
	v_pk_fma_f32 v[42:43], v[12:13], v[50:51], v[42:43]
	s_nop 0
	v_mul_f32_e32 v37, 0xbfb8aa3b, v42
	v_exp_f32_e32 v72, v37
	v_mul_f32_e32 v37, 0xbfb8aa3b, v43
	v_exp_f32_e32 v73, v37
	s_nop 0
	v_pk_add_f32 v[72:73], v[72:73], 1.0 op_sel_hi:[1,0]
	s_nop 0
	v_rcp_f32_e32 v71, v73
	s_nop 0
	v_mul_f32_e32 v43, v43, v71
	v_rcp_f32_e32 v71, v72
	s_nop 0
	v_mul_f32_e32 v42, v42, v71
	v_add_f32_e32 v37, v64, v65
	v_add_f32_e32 v37, v56, v37
	v_add_f32_e32 v37, v57, v37
	v_add_f32_e32 v37, v44, v37
	v_pk_mul_f32 v[72:73], v[42:43], v[42:43]
	v_add_f32_e32 v37, v45, v37
	v_add_f32_e32 v37, v72, v37
	v_add_f32_e32 v44, v73, v37
	v_cvt_pk_bf16_f32 v37, v42, v43
	v_lshlrev_b32_e32 v43, 8, v70
	v_add_f32_dpp v42, v44, v44 quad_perm:[1,0,3,2] row_mask:0xf bank_mask:0xf bound_ctrl:1
	s_nop 1
	v_add_f32_dpp v42, v42, v42 quad_perm:[2,3,0,1] row_mask:0xf bank_mask:0xf bound_ctrl:1
	s_nop 1
	v_add_f32_dpp v42, v42, v42 row_half_mirror row_mask:0xf bank_mask:0xf bound_ctrl:1
	s_nop 1
	v_add_f32_dpp v42, v42, v42 row_mirror row_mask:0xf bank_mask:0xf bound_ctrl:1
	s_and_saveexec_b64 s[38:39], s[10:11]
	s_xor_b64 s[38:39], exec, s[38:39]
	s_cbranch_execz .LBB0_237
	s_and_saveexec_b64 s[46:47], s[8:9]
	s_xor_b64 s[46:47], exec, s[46:47]
	v_add_u32_e32 v42, v232, v43
	ds_write_b128 v42, v[34:37] offset:33024
	s_andn2_saveexec_b64 s[46:47], s[46:47]
	s_cbranch_execz .LBB0_236
	v_lshlrev_b32_e32 v44, 4, v46
	v_xad_u32 v43, v44, 48, v43
	ds_write_b128 v43, v[34:37] offset:16640
	s_and_saveexec_b64 s[48:49], s[6:7]
	v_lshl_add_u32 v34, v70, 2, v224
	ds_write_b32 v34, v42
	s_or_b64 exec, exec, s[48:49]

; DI float siluf(float z) { return z / (1.f + __expf(-z)); }
; DI void phase_gdn_prep(const Params& p, int bid, int nb, char* smem) {
;     ...
; #pragma unroll
;       for (int i = 0; i < 16; i++) {
;         const int row = r0 + i;
;         float cur[8], o8[8];
;         unpack8(*(const u32x4*)(p.gqkv + (size_t)(t0 + row) * 1536 + gcol), cur);
;         float ss = 0.f;
; #pragma unroll
;         for (int e = 0; e < 8; e++) {
;           float v = cw[0][e] * w0[e] + cw[1][e] * w1[e] + cw[2][e] * w2[e] + cw[3][e] * cur[e];
;           v = siluf(v);
;           o8[e] = v; ss += v * v;
;           w0[e] = w1[e]; w1[e] = w2[e]; w2[e] = cur[e];
;         }
;         u32x4 pk = pack8(o8);
;         ss = sum16(ss);
;         if (tensor == 0) { *(u32x4*)(Qs + sw256(row, ch)) = pk; if (ch == 0) sSq[row] = ss; }
;         else if (tensor == 1) { *(u32x4*)(Ks + sw256(row, ch)) = pk; if (ch == 0) sSk[row] = ss; }
;         else { *(u32x4*)(Vs + row * 128 + ch * 8) = pk; }
;       }
.LBB0_241:
	s_or_b64 exec, exec, s[38:39]
	v_readlane_b32 s56, v253, 49
	v_or_b32_e32 v70, 4, v233
	v_readlane_b32 s62, v253, 55
	v_readlane_b32 s63, v253, 56
	v_add_u32_e32 v36, s77, v70
	v_readlane_b32 s57, v253, 50
	v_mov_b64_e32 v[34:35], s[62:63]
	v_mad_i64_i32 v[34:35], s[38:39], v36, s81, v[34:35]
	v_lshl_add_u64 v[34:35], v[48:49], 1, v[34:35]
	global_load_dwordx4 v[34:37], v[34:35], off
	v_readlane_b32 s58, v253, 51
	v_readlane_b32 s59, v253, 52
	v_readlane_b32 s60, v253, 53
	v_readlane_b32 s61, v253, 54
	v_readlane_b32 s64, v253, 57
	v_readlane_b32 s65, v253, 58
	v_readlane_b32 s66, v253, 59
	v_readlane_b32 s67, v253, 60
	v_readlane_b32 s68, v253, 61
	v_readlane_b32 s69, v253, 62
	v_readlane_b32 s70, v253, 63
	v_readlane_b32 s71, v252, 0
	s_waitcnt vmcnt(0)
	v_lshlrev_b32_e32 v72, 16, v34
	v_and_b32_e32 v73, 0xffff0000, v34
	v_lshlrev_b32_e32 v64, 16, v35
	v_and_b32_e32 v65, 0xffff0000, v35
	v_pk_mul_f32 v[34:35], v[30:31], v[76:77]
	v_lshlrev_b32_e32 v56, 16, v36
	v_pk_fma_f32 v[34:35], v[14:15], v[62:63], v[34:35]
	v_and_b32_e32 v57, 0xffff0000, v36
	v_pk_fma_f32 v[34:35], v[18:19], v[74:75], v[34:35]
	v_lshlrev_b32_e32 v44, 16, v37
	v_pk_fma_f32 v[34:35], v[22:23], v[72:73], v[34:35]
	v_and_b32_e32 v45, 0xffff0000, v37
	v_mul_f32_e32 v36, 0xbfb8aa3b, v34
	v_mul_f32_e32 v37, 0xbfb8aa3b, v35
	v_exp_f32_e32 v36, v36
	v_exp_f32_e32 v37, v37
	s_nop 0
	v_pk_add_f32 v[36:37], v[36:37], 1.0 op_sel_hi:[1,0]
	s_nop 0
	v_rcp_f32_e32 v43, v37
	s_nop 0
	v_mul_f32_e32 v35, v35, v43
	v_rcp_f32_e32 v42, v36
	s_nop 0
	v_mul_f32_e32 v34, v34, v42
	v_pk_mul_f32 v[36:37], v[32:33], v[68:69]
	v_pk_mul_f32 v[42:43], v[34:35], v[34:35]
	v_pk_fma_f32 v[36:37], v[16:17], v[54:55], v[36:37]
	v_cvt_pk_bf16_f32 v34, v34, v35
	v_pk_fma_f32 v[36:37], v[20:21], v[66:67], v[36:37]
	s_nop 0
	v_pk_fma_f32 v[36:37], v[24:25], v[64:65], v[36:37]
	s_nop 0
	v_mul_f32_e32 v35, 0xbfb8aa3b, v36
	v_exp_f32_e32 v54, v35
	v_mul_f32_e32 v35, 0xbfb8aa3b, v37
	v_exp_f32_e32 v55, v35
	s_nop 0
	v_pk_add_f32 v[54:55], v[54:55], 1.0 op_sel_hi:[1,0]
	s_nop 0
	v_rcp_f32_e32 v62, v55
	s_nop 0
	v_mul_f32_e32 v37, v37, v62
	v_rcp_f32_e32 v55, v54
	s_nop 0
	v_mul_f32_e32 v36, v36, v55
	v_pk_mul_f32 v[54:55], v[36:37], v[36:37]
	v_cvt_pk_bf16_f32 v35, v36, v37
	v_pk_mul_f32 v[36:37], v[26:27], v[60:61]
	s_nop 0
	v_pk_fma_f32 v[36:37], v[2:3], v[52:53], v[36:37]
	s_nop 0
	v_pk_fma_f32 v[36:37], v[6:7], v[58:59], v[36:37]
	s_nop 0
	v_pk_fma_f32 v[36:37], v[10:11], v[56:57], v[36:37]
	s_nop 0
	v_mul_f32_e32 v52, 0xbfb8aa3b, v36
	v_mul_f32_e32 v53, 0xbfb8aa3b, v37
	v_exp_f32_e32 v52, v52
	v_exp_f32_e32 v53, v53
	s_nop 0
	v_pk_add_f32 v[52:53], v[52:53], 1.0 op_sel_hi:[1,0]
	s_nop 0
	v_rcp_f32_e32 v63, v53
	s_nop 0
	v_mul_f32_e32 v37, v37, v63
	v_div_scale_f32 v53, s[38:39], v52, v52, v36
	v_rcp_f32_e32 v62, v53
	s_nop 0
	v_fma_f32 v63, -v53, v62, 1.0
	v_fmac_f32_e32 v62, v63, v62
	v_div_scale_f32 v63, vcc, v36, v52, v36
	v_mul_f32_e32 v71, v63, v62
	v_fma_f32 v235, -v53, v71, v63
	v_fmac_f32_e32 v71, v235, v62
	v_fma_f32 v53, -v53, v71, v63
	v_div_fmas_f32 v53, v53, v62, v71
	v_pk_mul_f32 v[62:63], v[28:29], v[40:41]
	v_div_fixup_f32 v36, v53, v52, v36
	v_pk_fma_f32 v[38:39], v[4:5], v[38:39], v[62:63]
	v_pk_mul_f32 v[52:53], v[36:37], v[36:37]
	v_pk_fma_f32 v[38:39], v[8:9], v[50:51], v[38:39]
	v_cvt_pk_bf16_f32 v36, v36, v37
	v_pk_fma_f32 v[38:39], v[12:13], v[44:45], v[38:39]
	s_nop 0
	v_mul_f32_e32 v37, 0xbfb8aa3b, v38
	v_exp_f32_e32 v62, v37
	v_mul_f32_e32 v37, 0xbfb8aa3b, v39
	v_exp_f32_e32 v63, v37
	s_nop 0
	v_pk_add_f32 v[62:63], v[62:63], 1.0 op_sel_hi:[1,0]
	s_nop 0
	v_rcp_f32_e32 v71, v63
	s_nop 0
	v_mul_f32_e32 v39, v39, v71
	v_rcp_f32_e32 v63, v62
	s_nop 0
	v_mul_f32_e32 v38, v38, v63
	v_add_f32_e32 v37, v42, v43
	v_add_f32_e32 v37, v54, v37
	v_add_f32_e32 v37, v55, v37
	v_add_f32_e32 v37, v52, v37
	v_pk_mul_f32 v[62:63], v[38:39], v[38:39]
	v_add_f32_e32 v37, v53, v37
	v_add_f32_e32 v37, v62, v37
	v_add_f32_e32 v42, v63, v37
	v_cvt_pk_bf16_f32 v37, v38, v39
	v_lshlrev_b32_e32 v39, 8, v70
	v_add_f32_dpp v38, v42, v42 quad_perm:[1,0,3,2] row_mask:0xf bank_mask:0xf bound_ctrl:1
	s_nop 1
	v_add_f32_dpp v38, v38, v38 quad_perm:[2,3,0,1] row_mask:0xf bank_mask:0xf bound_ctrl:1
	s_nop 1
	v_add_f32_dpp v38, v38, v38 row_half_mirror row_mask:0xf bank_mask:0xf bound_ctrl:1
	s_nop 1
	v_add_f32_dpp v38, v38, v38 row_mirror row_mask:0xf bank_mask:0xf bound_ctrl:1
	s_and_saveexec_b64 s[38:39], s[10:11]
	s_xor_b64 s[38:39], exec, s[38:39]
	s_cbranch_execz .LBB0_249
	s_and_saveexec_b64 s[46:47], s[8:9]
	s_xor_b64 s[46:47], exec, s[46:47]
	v_add_u32_e32 v38, v232, v39
	ds_write_b128 v38, v[34:37] offset:33024
	s_andn2_saveexec_b64 s[46:47], s[46:47]
	s_cbranch_execz .LBB0_248
	v_lshlrev_b32_e32 v42, 4, v46
	v_xad_u32 v39, v42, 64, v39
	ds_write_b128 v39, v[34:37] offset:16640
	s_and_saveexec_b64 s[48:49], s[6:7]
	v_lshl_add_u32 v34, v70, 2, v224
	ds_write_b32 v34, v38
	s_or_b64 exec, exec, s[48:49]

; DI float siluf(float z) { return z / (1.f + __expf(-z)); }
; DI void phase_gdn_prep(const Params& p, int bid, int nb, char* smem) {
;     ...
; #pragma unroll
;       for (int i = 0; i < 16; i++) {
;         const int row = r0 + i;
;         float cur[8], o8[8];
;         unpack8(*(const u32x4*)(p.gqkv + (size_t)(t0 + row) * 1536 + gcol), cur);
;         float ss = 0.f;
; #pragma unroll
;         for (int e = 0; e < 8; e++) {
;           float v = cw[0][e] * w0[e] + cw[1][e] * w1[e] + cw[2][e] * w2[e] + cw[3][e] * cur[e];
;           v = siluf(v);
;           o8[e] = v; ss += v * v;
;           w0[e] = w1[e]; w1[e] = w2[e]; w2[e] = cur[e];
;         }
;         u32x4 pk = pack8(o8);
;         ss = sum16(ss);
;         if (tensor == 0) { *(u32x4*)(Qs + sw256(row, ch)) = pk; if (ch == 0) sSq[row] = ss; }
;         else if (tensor == 1) { *(u32x4*)(Ks + sw256(row, ch)) = pk; if (ch == 0) sSk[row] = ss; }
;         else { *(u32x4*)(Vs + row * 128 + ch * 8) = pk; }
;       }
.LBB0_253:
	s_or_b64 exec, exec, s[38:39]
	v_readlane_b32 s56, v253, 49
	v_or_b32_e32 v235, 5, v233
	v_readlane_b32 s62, v253, 55
	v_readlane_b32 s63, v253, 56
	v_add_u32_e32 v36, s77, v235
	v_readlane_b32 s57, v253, 50
	v_mov_b64_e32 v[34:35], s[62:63]
	v_mad_i64_i32 v[34:35], s[38:39], v36, s81, v[34:35]
	v_lshl_add_u64 v[34:35], v[48:49], 1, v[34:35]
	global_load_dwordx4 v[34:37], v[34:35], off
	v_readlane_b32 s58, v253, 51
	v_readlane_b32 s59, v253, 52
	v_readlane_b32 s60, v253, 53
	v_readlane_b32 s61, v253, 54
	v_readlane_b32 s64, v253, 57
	v_readlane_b32 s65, v253, 58
	v_readlane_b32 s66, v253, 59
	v_readlane_b32 s67, v253, 60
	v_readlane_b32 s68, v253, 61
	v_readlane_b32 s69, v253, 62
	v_readlane_b32 s70, v253, 63
	v_readlane_b32 s71, v252, 0
	s_waitcnt vmcnt(0)
	v_lshlrev_b32_e32 v70, 16, v34
	v_and_b32_e32 v71, 0xffff0000, v34
	v_lshlrev_b32_e32 v62, 16, v35
	v_and_b32_e32 v63, 0xffff0000, v35
	v_pk_mul_f32 v[34:35], v[30:31], v[74:75]
	v_lshlrev_b32_e32 v54, 16, v36
	v_pk_fma_f32 v[34:35], v[14:15], v[76:77], v[34:35]
	v_and_b32_e32 v55, 0xffff0000, v36
	v_pk_fma_f32 v[34:35], v[18:19], v[72:73], v[34:35]
	v_lshlrev_b32_e32 v42, 16, v37
	v_pk_fma_f32 v[34:35], v[22:23], v[70:71], v[34:35]
	v_and_b32_e32 v43, 0xffff0000, v37
	v_mul_f32_e32 v36, 0xbfb8aa3b, v34
	v_mul_f32_e32 v37, 0xbfb8aa3b, v35
	v_exp_f32_e32 v36, v36
	v_exp_f32_e32 v37, v37
	s_nop 0
	v_pk_add_f32 v[36:37], v[36:37], 1.0 op_sel_hi:[1,0]
	s_nop 0
	v_rcp_f32_e32 v39, v37
	s_nop 0
	v_mul_f32_e32 v35, v35, v39
	v_rcp_f32_e32 v38, v36
	s_nop 0
	v_mul_f32_e32 v34, v34, v38
	v_pk_mul_f32 v[36:37], v[32:33], v[66:67]
	v_pk_mul_f32 v[38:39], v[34:35], v[34:35]
	v_pk_fma_f32 v[36:37], v[16:17], v[68:69], v[36:37]
	v_cvt_pk_bf16_f32 v34, v34, v35
	v_pk_fma_f32 v[36:37], v[20:21], v[64:65], v[36:37]
	s_nop 0
	v_pk_fma_f32 v[36:37], v[24:25], v[62:63], v[36:37]
	s_nop 0
	v_mul_f32_e32 v35, 0xbfb8aa3b, v36
	v_exp_f32_e32 v52, v35
	v_mul_f32_e32 v35, 0xbfb8aa3b, v37
	v_exp_f32_e32 v53, v35
	s_nop 0
	v_pk_add_f32 v[52:53], v[52:53], 1.0 op_sel_hi:[1,0]
	s_nop 0
	v_rcp_f32_e32 v68, v53
	s_nop 0
	v_mul_f32_e32 v37, v37, v68
	v_rcp_f32_e32 v53, v52
	s_nop 0
	v_mul_f32_e32 v36, v36, v53
	v_pk_mul_f32 v[52:53], v[36:37], v[36:37]
	v_cvt_pk_bf16_f32 v35, v36, v37
	v_pk_mul_f32 v[36:37], v[26:27], v[58:59]
	s_nop 0
	v_pk_fma_f32 v[36:37], v[2:3], v[60:61], v[36:37]
	s_nop 0
	v_pk_fma_f32 v[36:37], v[6:7], v[56:57], v[36:37]
	s_nop 0
	v_pk_fma_f32 v[36:37], v[10:11], v[54:55], v[36:37]
	s_nop 0
	v_mul_f32_e32 v60, 0xbfb8aa3b, v36
	v_mul_f32_e32 v61, 0xbfb8aa3b, v37
	v_exp_f32_e32 v60, v60
	v_exp_f32_e32 v61, v61
	s_nop 0
	v_pk_add_f32 v[60:61], v[60:61], 1.0 op_sel_hi:[1,0]
	s_nop 0
	v_rcp_f32_e32 v69, v61
	s_nop 0
	v_mul_f32_e32 v37, v37, v69
	v_div_scale_f32 v61, s[38:39], v60, v60, v36
	v_rcp_f32_e32 v68, v61
	s_nop 0
	v_fma_f32 v69, -v61, v68, 1.0
	v_fmac_f32_e32 v68, v69, v68
	v_div_scale_f32 v69, vcc, v36, v60, v36
	v_mul_f32_e32 v76, v69, v68
	v_fma_f32 v77, -v61, v76, v69
	v_fmac_f32_e32 v76, v77, v68
	v_fma_f32 v61, -v61, v76, v69
	v_div_fmas_f32 v61, v61, v68, v76
	v_pk_mul_f32 v[68:69], v[28:29], v[50:51]
	v_div_fixup_f32 v36, v61, v60, v36
	v_pk_fma_f32 v[40:41], v[4:5], v[40:41], v[68:69]
	v_pk_mul_f32 v[60:61], v[36:37], v[36:37]
	v_pk_fma_f32 v[40:41], v[8:9], v[44:45], v[40:41]
	v_cvt_pk_bf16_f32 v36, v36, v37
	v_pk_fma_f32 v[40:41], v[12:13], v[42:43], v[40:41]
	s_nop 0
	v_mul_f32_e32 v37, 0xbfb8aa3b, v40
	v_exp_f32_e32 v68, v37
	v_mul_f32_e32 v37, 0xbfb8aa3b, v41
	v_exp_f32_e32 v69, v37
	s_nop 0
	v_pk_add_f32 v[68:69], v[68:69], 1.0 op_sel_hi:[1,0]
	s_nop 0
	v_rcp_f32_e32 v76, v69
	s_nop 0
	v_mul_f32_e32 v41, v41, v76
	v_rcp_f32_e32 v69, v68
	s_nop 0
	v_mul_f32_e32 v40, v40, v69
	v_add_f32_e32 v37, v38, v39
	v_add_f32_e32 v37, v52, v37
	v_add_f32_e32 v37, v53, v37
	v_add_f32_e32 v37, v60, v37
	v_pk_mul_f32 v[68:69], v[40:41], v[40:41]
	v_add_f32_e32 v37, v61, v37
	v_add_f32_e32 v37, v68, v37
	v_add_f32_e32 v38, v69, v37
	v_cvt_pk_bf16_f32 v37, v40, v41
	v_lshlrev_b32_e32 v39, 8, v235
	v_add_f32_dpp v38, v38, v38 quad_perm:[1,0,3,2] row_mask:0xf bank_mask:0xf bound_ctrl:1
	s_nop 1
	v_add_f32_dpp v38, v38, v38 quad_perm:[2,3,0,1] row_mask:0xf bank_mask:0xf bound_ctrl:1
	s_nop 1
	v_add_f32_dpp v38, v38, v38 row_half_mirror row_mask:0xf bank_mask:0xf bound_ctrl:1
	s_nop 1
	v_add_f32_dpp v38, v38, v38 row_mirror row_mask:0xf bank_mask:0xf bound_ctrl:1
	s_and_saveexec_b64 s[38:39], s[10:11]
	s_xor_b64 s[38:39], exec, s[38:39]
	s_cbranch_execz .LBB0_261
	s_and_saveexec_b64 s[46:47], s[8:9]
	s_xor_b64 s[46:47], exec, s[46:47]
	v_add_u32_e32 v38, v232, v39
	ds_write_b128 v38, v[34:37] offset:33024
	s_andn2_saveexec_b64 s[46:47], s[46:47]
	s_cbranch_execz .LBB0_260
	v_lshlrev_b32_e32 v40, 4, v46
	v_xad_u32 v39, v40, s82, v39
	ds_write_b128 v39, v[34:37] offset:16640
	s_and_saveexec_b64 s[48:49], s[6:7]
	v_lshl_add_u32 v34, v235, 2, v224
	ds_write_b32 v34, v38
	s_or_b64 exec, exec, s[48:49]

; DI float siluf(float z) { return z / (1.f + __expf(-z)); }
; DI void phase_gdn_prep(const Params& p, int bid, int nb, char* smem) {
;     ...
; #pragma unroll
;       for (int i = 0; i < 16; i++) {
;         const int row = r0 + i;
;         float cur[8], o8[8];
;         unpack8(*(const u32x4*)(p.gqkv + (size_t)(t0 + row) * 1536 + gcol), cur);
;         float ss = 0.f;
; #pragma unroll
;         for (int e = 0; e < 8; e++) {
;           float v = cw[0][e] * w0[e] + cw[1][e] * w1[e] + cw[2][e] * w2[e] + cw[3][e] * cur[e];
;           v = siluf(v);
;           o8[e] = v; ss += v * v;
;           w0[e] = w1[e]; w1[e] = w2[e]; w2[e] = cur[e];
;         }
;         u32x4 pk = pack8(o8);
;         ss = sum16(ss);
;         if (tensor == 0) { *(u32x4*)(Qs + sw256(row, ch)) = pk; if (ch == 0) sSq[row] = ss; }
;         else if (tensor == 1) { *(u32x4*)(Ks + sw256(row, ch)) = pk; if (ch == 0) sSk[row] = ss; }
;         else { *(u32x4*)(Vs + row * 128 + ch * 8) = pk; }
;       }
.LBB0_265:
	s_or_b64 exec, exec, s[38:39]
	v_readlane_b32 s56, v253, 49
	v_or_b32_e32 v76, 6, v233
	v_readlane_b32 s62, v253, 55
	v_readlane_b32 s63, v253, 56
	v_add_u32_e32 v36, s77, v76
	v_readlane_b32 s57, v253, 50
	v_mov_b64_e32 v[34:35], s[62:63]
	v_mad_i64_i32 v[34:35], s[38:39], v36, s81, v[34:35]
	v_lshl_add_u64 v[34:35], v[48:49], 1, v[34:35]
	global_load_dwordx4 v[34:37], v[34:35], off
	v_readlane_b32 s58, v253, 51
	v_readlane_b32 s59, v253, 52
	v_readlane_b32 s60, v253, 53
	v_readlane_b32 s61, v253, 54
	v_readlane_b32 s64, v253, 57
	v_readlane_b32 s65, v253, 58
	v_readlane_b32 s66, v253, 59
	v_readlane_b32 s67, v253, 60
	v_readlane_b32 s68, v253, 61
	v_readlane_b32 s69, v253, 62
	v_readlane_b32 s70, v253, 63
	v_readlane_b32 s71, v252, 0
	s_waitcnt vmcnt(0)
	v_lshlrev_b32_e32 v68, 16, v34
	v_and_b32_e32 v69, 0xffff0000, v34
	v_lshlrev_b32_e32 v60, 16, v35
	v_and_b32_e32 v61, 0xffff0000, v35
	v_pk_mul_f32 v[34:35], v[30:31], v[72:73]
	v_lshlrev_b32_e32 v52, 16, v36
	v_pk_fma_f32 v[34:35], v[14:15], v[74:75], v[34:35]
	v_and_b32_e32 v53, 0xffff0000, v36
	v_pk_fma_f32 v[34:35], v[18:19], v[70:71], v[34:35]
	v_lshlrev_b32_e32 v40, 16, v37
	v_pk_fma_f32 v[34:35], v[22:23], v[68:69], v[34:35]
	v_and_b32_e32 v41, 0xffff0000, v37
	v_mul_f32_e32 v36, 0xbfb8aa3b, v34
	v_mul_f32_e32 v37, 0xbfb8aa3b, v35
	v_exp_f32_e32 v36, v36
	v_exp_f32_e32 v37, v37
	s_nop 0
	v_pk_add_f32 v[36:37], v[36:37], 1.0 op_sel_hi:[1,0]
	s_nop 0
	v_rcp_f32_e32 v39, v37
	s_nop 0
	v_mul_f32_e32 v35, v35, v39
	v_rcp_f32_e32 v38, v36
	s_nop 0
	v_mul_f32_e32 v34, v34, v38
	v_pk_mul_f32 v[36:37], v[32:33], v[64:65]
	v_pk_mul_f32 v[38:39], v[34:35], v[34:35]
	v_pk_fma_f32 v[36:37], v[16:17], v[66:67], v[36:37]
	v_cvt_pk_bf16_f32 v34, v34, v35
	v_pk_fma_f32 v[36:37], v[20:21], v[62:63], v[36:37]
	s_nop 0
	v_pk_fma_f32 v[36:37], v[24:25], v[60:61], v[36:37]
	s_nop 0
	v_mul_f32_e32 v35, 0xbfb8aa3b, v36
	v_exp_f32_e32 v66, v35
	v_mul_f32_e32 v35, 0xbfb8aa3b, v37
	v_exp_f32_e32 v67, v35
	s_nop 0
	v_pk_add_f32 v[66:67], v[66:67], 1.0 op_sel_hi:[1,0]
	s_nop 0
	v_rcp_f32_e32 v74, v67
	s_nop 0
	v_mul_f32_e32 v37, v37, v74
	v_rcp_f32_e32 v67, v66
	s_nop 0
	v_mul_f32_e32 v36, v36, v67
	v_pk_mul_f32 v[66:67], v[36:37], v[36:37]
	v_cvt_pk_bf16_f32 v35, v36, v37
	v_pk_mul_f32 v[36:37], v[26:27], v[56:57]
	s_nop 0
	v_pk_fma_f32 v[36:37], v[2:3], v[58:59], v[36:37]
	s_nop 0
	v_pk_fma_f32 v[36:37], v[6:7], v[54:55], v[36:37]
	s_nop 0
	v_pk_fma_f32 v[36:37], v[10:11], v[52:53], v[36:37]
	s_nop 0
	v_mul_f32_e32 v58, 0xbfb8aa3b, v36
	v_mul_f32_e32 v59, 0xbfb8aa3b, v37
	v_exp_f32_e32 v58, v58
	v_exp_f32_e32 v59, v59
	s_nop 0
	v_pk_add_f32 v[58:59], v[58:59], 1.0 op_sel_hi:[1,0]
	s_nop 0
	v_rcp_f32_e32 v75, v59
	s_nop 0
	v_mul_f32_e32 v37, v37, v75
	v_div_scale_f32 v59, s[38:39], v58, v58, v36
	v_rcp_f32_e32 v74, v59
	s_nop 0
	v_fma_f32 v75, -v59, v74, 1.0
	v_fmac_f32_e32 v74, v75, v74
	v_div_scale_f32 v75, vcc, v36, v58, v36
	v_mul_f32_e32 v77, v75, v74
	v_fma_f32 v235, -v59, v77, v75
	v_fmac_f32_e32 v77, v235, v74
	v_fma_f32 v59, -v59, v77, v75
	v_div_fmas_f32 v59, v59, v74, v77
	v_pk_mul_f32 v[74:75], v[28:29], v[44:45]
	v_div_fixup_f32 v36, v59, v58, v36
	v_pk_fma_f32 v[50:51], v[4:5], v[50:51], v[74:75]
	v_pk_mul_f32 v[58:59], v[36:37], v[36:37]
	v_pk_fma_f32 v[50:51], v[8:9], v[42:43], v[50:51]
	v_cvt_pk_bf16_f32 v36, v36, v37
	v_pk_fma_f32 v[50:51], v[12:13], v[40:41], v[50:51]
	s_nop 0
	v_mul_f32_e32 v37, 0xbfb8aa3b, v50
	v_exp_f32_e32 v74, v37
	v_mul_f32_e32 v37, 0xbfb8aa3b, v51
	v_exp_f32_e32 v75, v37
	s_nop 0
	v_pk_add_f32 v[74:75], v[74:75], 1.0 op_sel_hi:[1,0]
	s_nop 0
	v_rcp_f32_e32 v77, v75
	s_nop 0
	v_mul_f32_e32 v51, v51, v77
	v_rcp_f32_e32 v75, v74
	s_nop 0
	v_mul_f32_e32 v50, v50, v75
	v_add_f32_e32 v37, v38, v39
	v_add_f32_e32 v37, v66, v37
	v_add_f32_e32 v37, v67, v37
	v_add_f32_e32 v37, v58, v37
	v_pk_mul_f32 v[74:75], v[50:51], v[50:51]
	v_add_f32_e32 v37, v59, v37
	v_add_f32_e32 v37, v74, v37
	v_add_f32_e32 v38, v75, v37
	v_cvt_pk_bf16_f32 v37, v50, v51
	v_lshlrev_b32_e32 v39, 8, v76
	v_add_f32_dpp v38, v38, v38 quad_perm:[1,0,3,2] row_mask:0xf bank_mask:0xf bound_ctrl:1
	s_nop 1
	v_add_f32_dpp v38, v38, v38 quad_perm:[2,3,0,1] row_mask:0xf bank_mask:0xf bound_ctrl:1
	s_nop 1
	v_add_f32_dpp v38, v38, v38 row_half_mirror row_mask:0xf bank_mask:0xf bound_ctrl:1
	s_nop 1
	v_add_f32_dpp v38, v38, v38 row_mirror row_mask:0xf bank_mask:0xf bound_ctrl:1
	s_and_saveexec_b64 s[38:39], s[10:11]
	s_xor_b64 s[38:39], exec, s[38:39]
	s_cbranch_execz .LBB0_273
	s_and_saveexec_b64 s[46:47], s[8:9]
	s_xor_b64 s[46:47], exec, s[46:47]
	v_add_u32_e32 v38, v232, v39
	ds_write_b128 v38, v[34:37] offset:33024
	s_andn2_saveexec_b64 s[46:47], s[46:47]
	s_cbranch_execz .LBB0_272
	v_lshlrev_b32_e32 v50, 4, v46
	v_xad_u32 v39, v50, s83, v39
	ds_write_b128 v39, v[34:37] offset:16640
	s_and_saveexec_b64 s[48:49], s[6:7]
	v_lshl_add_u32 v34, v76, 2, v224
	ds_write_b32 v34, v38
	s_or_b64 exec, exec, s[48:49]

; DI float siluf(float z) { return z / (1.f + __expf(-z)); }
; DI void phase_gdn_prep(const Params& p, int bid, int nb, char* smem) {
;     ...
; #pragma unroll
;       for (int i = 0; i < 16; i++) {
;         const int row = r0 + i;
;         float cur[8], o8[8];
;         unpack8(*(const u32x4*)(p.gqkv + (size_t)(t0 + row) * 1536 + gcol), cur);
;         float ss = 0.f;
; #pragma unroll
;         for (int e = 0; e < 8; e++) {
;           float v = cw[0][e] * w0[e] + cw[1][e] * w1[e] + cw[2][e] * w2[e] + cw[3][e] * cur[e];
;           v = siluf(v);
;           o8[e] = v; ss += v * v;
;           w0[e] = w1[e]; w1[e] = w2[e]; w2[e] = cur[e];
;         }
;         u32x4 pk = pack8(o8);
;         ss = sum16(ss);
;         if (tensor == 0) { *(u32x4*)(Qs + sw256(row, ch)) = pk; if (ch == 0) sSq[row] = ss; }
;         else if (tensor == 1) { *(u32x4*)(Ks + sw256(row, ch)) = pk; if (ch == 0) sSk[row] = ss; }
;         else { *(u32x4*)(Vs + row * 128 + ch * 8) = pk; }
;       }
.LBB0_277:
	s_or_b64 exec, exec, s[38:39]
	v_readlane_b32 s56, v253, 49
	v_or_b32_e32 v74, 7, v233
	v_readlane_b32 s62, v253, 55
	v_readlane_b32 s63, v253, 56
	v_add_u32_e32 v36, s77, v74
	v_readlane_b32 s57, v253, 50
	v_mov_b64_e32 v[34:35], s[62:63]
	v_mad_i64_i32 v[34:35], s[38:39], v36, s81, v[34:35]
	v_lshl_add_u64 v[34:35], v[48:49], 1, v[34:35]
	global_load_dwordx4 v[34:37], v[34:35], off
	v_readlane_b32 s58, v253, 51
	v_readlane_b32 s59, v253, 52
	v_readlane_b32 s60, v253, 53
	v_readlane_b32 s61, v253, 54
	v_readlane_b32 s64, v253, 57
	v_readlane_b32 s65, v253, 58
	v_readlane_b32 s66, v253, 59
	v_readlane_b32 s67, v253, 60
	v_readlane_b32 s68, v253, 61
	v_readlane_b32 s69, v253, 62
	v_readlane_b32 s70, v253, 63
	v_readlane_b32 s71, v252, 0
	s_waitcnt vmcnt(0)
	v_lshlrev_b32_e32 v66, 16, v34
	v_and_b32_e32 v67, 0xffff0000, v34
	v_lshlrev_b32_e32 v58, 16, v35
	v_and_b32_e32 v59, 0xffff0000, v35
	v_pk_mul_f32 v[34:35], v[30:31], v[70:71]
	v_lshlrev_b32_e32 v50, 16, v36
	v_pk_fma_f32 v[34:35], v[14:15], v[72:73], v[34:35]
	v_and_b32_e32 v51, 0xffff0000, v36
	v_pk_fma_f32 v[34:35], v[18:19], v[68:69], v[34:35]
	v_lshlrev_b32_e32 v38, 16, v37
	v_pk_fma_f32 v[34:35], v[22:23], v[66:67], v[34:35]
	v_and_b32_e32 v39, 0xffff0000, v37
	v_mul_f32_e32 v36, 0xbfb8aa3b, v34
	v_mul_f32_e32 v37, 0xbfb8aa3b, v35
	v_exp_f32_e32 v36, v36
	v_exp_f32_e32 v37, v37
	s_nop 0
	v_pk_add_f32 v[36:37], v[36:37], 1.0 op_sel_hi:[1,0]
	s_nop 0
	v_rcp_f32_e32 v73, v37
	s_nop 0
	v_mul_f32_e32 v35, v35, v73
	v_rcp_f32_e32 v72, v36
	s_nop 0
	v_mul_f32_e32 v34, v34, v72
	v_pk_mul_f32 v[36:37], v[32:33], v[62:63]
	v_pk_mul_f32 v[72:73], v[34:35], v[34:35]
	v_pk_fma_f32 v[36:37], v[16:17], v[64:65], v[36:37]
	v_cvt_pk_bf16_f32 v34, v34, v35
	v_pk_fma_f32 v[36:37], v[20:21], v[60:61], v[36:37]
	s_nop 0
	v_pk_fma_f32 v[36:37], v[24:25], v[58:59], v[36:37]
	s_nop 0
	v_mul_f32_e32 v35, 0xbfb8aa3b, v36
	v_exp_f32_e32 v64, v35
	v_mul_f32_e32 v35, 0xbfb8aa3b, v37
	v_exp_f32_e32 v65, v35
	s_nop 0
	v_pk_add_f32 v[64:65], v[64:65], 1.0 op_sel_hi:[1,0]
	s_nop 0
	v_rcp_f32_e32 v75, v65
	s_nop 0
	v_mul_f32_e32 v37, v37, v75
	v_rcp_f32_e32 v65, v64
	s_nop 0
	v_mul_f32_e32 v36, v36, v65
	v_pk_mul_f32 v[64:65], v[36:37], v[36:37]
	v_cvt_pk_bf16_f32 v35, v36, v37
	v_pk_mul_f32 v[36:37], v[26:27], v[54:55]
	s_nop 0
	v_pk_fma_f32 v[36:37], v[2:3], v[56:57], v[36:37]
	s_nop 0
	v_pk_fma_f32 v[36:37], v[6:7], v[52:53], v[36:37]
	s_nop 0
	v_pk_fma_f32 v[36:37], v[10:11], v[50:51], v[36:37]
	s_nop 0
	v_mul_f32_e32 v56, 0xbfb8aa3b, v36
	v_mul_f32_e32 v57, 0xbfb8aa3b, v37
	v_exp_f32_e32 v56, v56
	v_exp_f32_e32 v57, v57
	s_nop 0
	v_pk_add_f32 v[56:57], v[56:57], 1.0 op_sel_hi:[1,0]
	s_nop 0
	v_rcp_f32_e32 v76, v57
	s_nop 0
	v_mul_f32_e32 v37, v37, v76
	v_div_scale_f32 v57, s[38:39], v56, v56, v36
	v_rcp_f32_e32 v75, v57
	s_nop 0
	v_fma_f32 v76, -v57, v75, 1.0
	v_fmac_f32_e32 v75, v76, v75
	v_div_scale_f32 v76, vcc, v36, v56, v36
	v_mul_f32_e32 v77, v76, v75
	v_fma_f32 v235, -v57, v77, v76
	v_fmac_f32_e32 v77, v235, v75
	v_fma_f32 v57, -v57, v77, v76
	v_div_fmas_f32 v57, v57, v75, v77
	v_pk_mul_f32 v[76:77], v[28:29], v[42:43]
	v_div_fixup_f32 v36, v57, v56, v36
	v_pk_fma_f32 v[44:45], v[4:5], v[44:45], v[76:77]
	v_pk_mul_f32 v[56:57], v[36:37], v[36:37]
	v_pk_fma_f32 v[44:45], v[8:9], v[40:41], v[44:45]
	v_cvt_pk_bf16_f32 v36, v36, v37
	v_pk_fma_f32 v[44:45], v[12:13], v[38:39], v[44:45]
	s_nop 0
	v_mul_f32_e32 v37, 0xbfb8aa3b, v44
	v_exp_f32_e32 v76, v37
	v_mul_f32_e32 v37, 0xbfb8aa3b, v45
	v_exp_f32_e32 v77, v37
	s_nop 0
	v_pk_add_f32 v[76:77], v[76:77], 1.0 op_sel_hi:[1,0]
	s_nop 0
	v_rcp_f32_e32 v75, v77
	s_nop 0
	v_mul_f32_e32 v45, v45, v75
	v_rcp_f32_e32 v75, v76
	s_nop 0
	v_mul_f32_e32 v44, v44, v75
	v_add_f32_e32 v37, v72, v73
	v_add_f32_e32 v37, v64, v37
	v_add_f32_e32 v37, v65, v37
	v_add_f32_e32 v37, v56, v37
	v_pk_mul_f32 v[76:77], v[44:45], v[44:45]
	v_add_f32_e32 v37, v57, v37
	v_add_f32_e32 v37, v76, v37
	v_add_f32_e32 v56, v77, v37
	v_cvt_pk_bf16_f32 v37, v44, v45
	v_lshlrev_b32_e32 v45, 8, v74
	v_add_f32_dpp v44, v56, v56 quad_perm:[1,0,3,2] row_mask:0xf bank_mask:0xf bound_ctrl:1
	s_nop 1
	v_add_f32_dpp v44, v44, v44 quad_perm:[2,3,0,1] row_mask:0xf bank_mask:0xf bound_ctrl:1
	s_nop 1
	v_add_f32_dpp v44, v44, v44 row_half_mirror row_mask:0xf bank_mask:0xf bound_ctrl:1
	s_nop 1
	v_add_f32_dpp v44, v44, v44 row_mirror row_mask:0xf bank_mask:0xf bound_ctrl:1
	s_and_saveexec_b64 s[38:39], s[10:11]
	s_xor_b64 s[38:39], exec, s[38:39]
	s_cbranch_execz .LBB0_285
	s_and_saveexec_b64 s[46:47], s[8:9]
	s_xor_b64 s[46:47], exec, s[46:47]
	v_add_u32_e32 v44, v232, v45
	ds_write_b128 v44, v[34:37] offset:33024
	s_andn2_saveexec_b64 s[46:47], s[46:47]
	s_cbranch_execz .LBB0_284
	v_lshlrev_b32_e32 v56, 4, v46
	v_xad_u32 v45, v56, s84, v45
	ds_write_b128 v45, v[34:37] offset:16640
	s_and_saveexec_b64 s[48:49], s[6:7]
	v_lshl_add_u32 v34, v74, 2, v224
	ds_write_b32 v34, v44
	s_or_b64 exec, exec, s[48:49]

; DI float siluf(float z) { return z / (1.f + __expf(-z)); }
; DI void phase_gdn_prep(const Params& p, int bid, int nb, char* smem) {
;     ...
; #pragma unroll
;       for (int i = 0; i < 16; i++) {
;         const int row = r0 + i;
;         float cur[8], o8[8];
;         unpack8(*(const u32x4*)(p.gqkv + (size_t)(t0 + row) * 1536 + gcol), cur);
;         float ss = 0.f;
; #pragma unroll
;         for (int e = 0; e < 8; e++) {
;           float v = cw[0][e] * w0[e] + cw[1][e] * w1[e] + cw[2][e] * w2[e] + cw[3][e] * cur[e];
;           v = siluf(v);
;           o8[e] = v; ss += v * v;
;           w0[e] = w1[e]; w1[e] = w2[e]; w2[e] = cur[e];
;         }
;         u32x4 pk = pack8(o8);
;         ss = sum16(ss);
;         if (tensor == 0) { *(u32x4*)(Qs + sw256(row, ch)) = pk; if (ch == 0) sSq[row] = ss; }
;         else if (tensor == 1) { *(u32x4*)(Ks + sw256(row, ch)) = pk; if (ch == 0) sSk[row] = ss; }
;         else { *(u32x4*)(Vs + row * 128 + ch * 8) = pk; }
;       }
.LBB0_289:
	s_or_b64 exec, exec, s[38:39]
	v_readlane_b32 s56, v253, 49
	v_or_b32_e32 v74, 8, v233
	v_readlane_b32 s62, v253, 55
	v_readlane_b32 s63, v253, 56
	v_add_u32_e32 v36, s77, v74
	v_readlane_b32 s57, v253, 50
	v_mov_b64_e32 v[34:35], s[62:63]
	v_mad_i64_i32 v[34:35], s[38:39], v36, s81, v[34:35]
	v_lshl_add_u64 v[34:35], v[48:49], 1, v[34:35]
	global_load_dwordx4 v[34:37], v[34:35], off
	v_readlane_b32 s58, v253, 51
	v_readlane_b32 s59, v253, 52
	v_readlane_b32 s60, v253, 53
	v_readlane_b32 s61, v253, 54
	v_readlane_b32 s64, v253, 57
	v_readlane_b32 s65, v253, 58
	v_readlane_b32 s66, v253, 59
	v_readlane_b32 s67, v253, 60
	v_readlane_b32 s68, v253, 61
	v_readlane_b32 s69, v253, 62
	v_readlane_b32 s70, v253, 63
	v_readlane_b32 s71, v252, 0
	s_waitcnt vmcnt(0)
	v_lshlrev_b32_e32 v72, 16, v34
	v_and_b32_e32 v73, 0xffff0000, v34
	v_lshlrev_b32_e32 v64, 16, v35
	v_and_b32_e32 v65, 0xffff0000, v35
	v_pk_mul_f32 v[34:35], v[30:31], v[68:69]
	v_lshlrev_b32_e32 v56, 16, v36
	v_pk_fma_f32 v[34:35], v[14:15], v[70:71], v[34:35]
	v_and_b32_e32 v57, 0xffff0000, v36
	v_pk_fma_f32 v[34:35], v[18:19], v[66:67], v[34:35]
	v_lshlrev_b32_e32 v44, 16, v37
	v_pk_fma_f32 v[34:35], v[22:23], v[72:73], v[34:35]
	v_and_b32_e32 v45, 0xffff0000, v37
	v_mul_f32_e32 v36, 0xbfb8aa3b, v34
	v_mul_f32_e32 v37, 0xbfb8aa3b, v35
	v_exp_f32_e32 v36, v36
	v_exp_f32_e32 v37, v37
	s_nop 0
	v_pk_add_f32 v[36:37], v[36:37], 1.0 op_sel_hi:[1,0]
	s_nop 0
	v_rcp_f32_e32 v71, v37
	s_nop 0
	v_mul_f32_e32 v35, v35, v71
	v_rcp_f32_e32 v70, v36
	s_nop 0
	v_mul_f32_e32 v34, v34, v70
	v_pk_mul_f32 v[36:37], v[32:33], v[60:61]
	v_pk_mul_f32 v[70:71], v[34:35], v[34:35]
	v_pk_fma_f32 v[36:37], v[16:17], v[62:63], v[36:37]
	v_cvt_pk_bf16_f32 v34, v34, v35
	v_pk_fma_f32 v[36:37], v[20:21], v[58:59], v[36:37]
	s_nop 0
	v_pk_fma_f32 v[36:37], v[24:25], v[64:65], v[36:37]
	s_nop 0
	v_mul_f32_e32 v35, 0xbfb8aa3b, v36
	v_exp_f32_e32 v62, v35
	v_mul_f32_e32 v35, 0xbfb8aa3b, v37
	v_exp_f32_e32 v63, v35
	s_nop 0
	v_pk_add_f32 v[62:63], v[62:63], 1.0 op_sel_hi:[1,0]
	s_nop 0
	v_rcp_f32_e32 v75, v63
	s_nop 0
	v_mul_f32_e32 v37, v37, v75
	v_rcp_f32_e32 v63, v62
	s_nop 0
	v_mul_f32_e32 v36, v36, v63
	v_pk_mul_f32 v[62:63], v[36:37], v[36:37]
	v_cvt_pk_bf16_f32 v35, v36, v37
	v_pk_mul_f32 v[36:37], v[26:27], v[52:53]
	s_nop 0
	v_pk_fma_f32 v[36:37], v[2:3], v[54:55], v[36:37]
	s_nop 0
	v_pk_fma_f32 v[36:37], v[6:7], v[50:51], v[36:37]
	s_nop 0
	v_pk_fma_f32 v[36:37], v[10:11], v[56:57], v[36:37]
	s_nop 0
	v_mul_f32_e32 v54, 0xbfb8aa3b, v36
	v_mul_f32_e32 v55, 0xbfb8aa3b, v37
	v_exp_f32_e32 v54, v54
	v_exp_f32_e32 v55, v55
	s_nop 0
	v_pk_add_f32 v[54:55], v[54:55], 1.0 op_sel_hi:[1,0]
	s_nop 0
	v_rcp_f32_e32 v76, v55
	s_nop 0
	v_mul_f32_e32 v37, v37, v76
	v_div_scale_f32 v55, s[38:39], v54, v54, v36
	v_rcp_f32_e32 v75, v55
	s_nop 0
	v_fma_f32 v76, -v55, v75, 1.0
	v_fmac_f32_e32 v75, v76, v75
	v_div_scale_f32 v76, vcc, v36, v54, v36
	v_mul_f32_e32 v77, v76, v75
	v_fma_f32 v235, -v55, v77, v76
	v_fmac_f32_e32 v77, v235, v75
	v_fma_f32 v55, -v55, v77, v76
	v_div_fmas_f32 v55, v55, v75, v77
	v_pk_mul_f32 v[76:77], v[28:29], v[40:41]
	v_div_fixup_f32 v36, v55, v54, v36
	v_pk_fma_f32 v[42:43], v[4:5], v[42:43], v[76:77]
	v_pk_mul_f32 v[54:55], v[36:37], v[36:37]
	v_pk_fma_f32 v[42:43], v[8:9], v[38:39], v[42:43]
	v_cvt_pk_bf16_f32 v36, v36, v37
	v_pk_fma_f32 v[42:43], v[12:13], v[44:45], v[42:43]
	s_nop 0
	v_mul_f32_e32 v37, 0xbfb8aa3b, v42
	v_exp_f32_e32 v76, v37
	v_mul_f32_e32 v37, 0xbfb8aa3b, v43
	v_exp_f32_e32 v77, v37
	s_nop 0
	v_pk_add_f32 v[76:77], v[76:77], 1.0 op_sel_hi:[1,0]
	s_nop 0
	v_rcp_f32_e32 v75, v77
	s_nop 0
	v_mul_f32_e32 v43, v43, v75
	v_rcp_f32_e32 v75, v76
	s_nop 0
	v_mul_f32_e32 v42, v42, v75
	v_add_f32_e32 v37, v70, v71
	v_add_f32_e32 v37, v62, v37
	v_add_f32_e32 v37, v63, v37
	v_add_f32_e32 v37, v54, v37
	v_pk_mul_f32 v[76:77], v[42:43], v[42:43]
	v_add_f32_e32 v37, v55, v37
	v_add_f32_e32 v37, v76, v37
	v_add_f32_e32 v54, v77, v37
	v_cvt_pk_bf16_f32 v37, v42, v43
	v_lshlrev_b32_e32 v43, 8, v74
	v_add_f32_dpp v42, v54, v54 quad_perm:[1,0,3,2] row_mask:0xf bank_mask:0xf bound_ctrl:1
	s_nop 1
	v_add_f32_dpp v42, v42, v42 quad_perm:[2,3,0,1] row_mask:0xf bank_mask:0xf bound_ctrl:1
	s_nop 1
	v_add_f32_dpp v42, v42, v42 row_half_mirror row_mask:0xf bank_mask:0xf bound_ctrl:1
	s_nop 1
	v_add_f32_dpp v42, v42, v42 row_mirror row_mask:0xf bank_mask:0xf bound_ctrl:1
	s_and_saveexec_b64 s[38:39], s[10:11]
	s_xor_b64 s[38:39], exec, s[38:39]
	s_cbranch_execz .LBB0_297
	s_and_saveexec_b64 s[46:47], s[8:9]
	s_xor_b64 s[46:47], exec, s[46:47]
	v_add_u32_e32 v42, v232, v43
	ds_write_b128 v42, v[34:37] offset:33024
	s_andn2_saveexec_b64 s[46:47], s[46:47]
	s_cbranch_execz .LBB0_296
	v_lshlrev_b32_e32 v54, 4, v46
	v_xad_u32 v43, v54, s3, v43
	ds_write_b128 v43, v[34:37] offset:16640
	s_and_saveexec_b64 s[48:49], s[6:7]
	v_lshl_add_u32 v34, v74, 2, v224
	ds_write_b32 v34, v42
	s_or_b64 exec, exec, s[48:49]

; DI float siluf(float z) { return z / (1.f + __expf(-z)); }
; DI void phase_gdn_prep(const Params& p, int bid, int nb, char* smem) {
;     ...
; #pragma unroll
;       for (int i = 0; i < 16; i++) {
;         const int row = r0 + i;
;         float cur[8], o8[8];
;         unpack8(*(const u32x4*)(p.gqkv + (size_t)(t0 + row) * 1536 + gcol), cur);
;         float ss = 0.f;
; #pragma unroll
;         for (int e = 0; e < 8; e++) {
;           float v = cw[0][e] * w0[e] + cw[1][e] * w1[e] + cw[2][e] * w2[e] + cw[3][e] * cur[e];
;           v = siluf(v);
;           o8[e] = v; ss += v * v;
;           w0[e] = w1[e]; w1[e] = w2[e]; w2[e] = cur[e];
;         }
;         u32x4 pk = pack8(o8);
;         ss = sum16(ss);
;         if (tensor == 0) { *(u32x4*)(Qs + sw256(row, ch)) = pk; if (ch == 0) sSq[row] = ss; }
;         else if (tensor == 1) { *(u32x4*)(Ks + sw256(row, ch)) = pk; if (ch == 0) sSk[row] = ss; }
;         else { *(u32x4*)(Vs + row * 128 + ch * 8) = pk; }
;       }
.LBB0_301:
	s_or_b64 exec, exec, s[38:39]
	v_readlane_b32 s56, v253, 49
	v_or_b32_e32 v74, 9, v233
	v_readlane_b32 s62, v253, 55
	v_readlane_b32 s63, v253, 56
	v_add_u32_e32 v36, s77, v74
	v_readlane_b32 s57, v253, 50
	v_mov_b64_e32 v[34:35], s[62:63]
	v_mad_i64_i32 v[34:35], s[38:39], v36, s81, v[34:35]
	v_lshl_add_u64 v[34:35], v[48:49], 1, v[34:35]
	global_load_dwordx4 v[34:37], v[34:35], off
	v_readlane_b32 s58, v253, 51
	v_readlane_b32 s59, v253, 52
	v_readlane_b32 s60, v253, 53
	v_readlane_b32 s61, v253, 54
	v_readlane_b32 s64, v253, 57
	v_readlane_b32 s65, v253, 58
	v_readlane_b32 s66, v253, 59
	v_readlane_b32 s67, v253, 60
	v_readlane_b32 s68, v253, 61
	v_readlane_b32 s69, v253, 62
	v_readlane_b32 s70, v253, 63
	v_readlane_b32 s71, v252, 0
	s_waitcnt vmcnt(0)
	v_lshlrev_b32_e32 v70, 16, v34
	v_and_b32_e32 v71, 0xffff0000, v34
	v_lshlrev_b32_e32 v62, 16, v35
	v_and_b32_e32 v63, 0xffff0000, v35
	v_pk_mul_f32 v[34:35], v[30:31], v[66:67]
	v_lshlrev_b32_e32 v54, 16, v36
	v_pk_fma_f32 v[34:35], v[14:15], v[68:69], v[34:35]
	v_and_b32_e32 v55, 0xffff0000, v36
	v_pk_fma_f32 v[34:35], v[18:19], v[72:73], v[34:35]
	v_lshlrev_b32_e32 v42, 16, v37
	v_pk_fma_f32 v[34:35], v[22:23], v[70:71], v[34:35]
	v_and_b32_e32 v43, 0xffff0000, v37
	v_mul_f32_e32 v36, 0xbfb8aa3b, v34
	v_mul_f32_e32 v37, 0xbfb8aa3b, v35
	v_exp_f32_e32 v36, v36
	v_exp_f32_e32 v37, v37
	s_nop 0
	v_pk_add_f32 v[36:37], v[36:37], 1.0 op_sel_hi:[1,0]
	s_nop 0
	v_rcp_f32_e32 v69, v37
	s_nop 0
	v_mul_f32_e32 v35, v35, v69
	v_rcp_f32_e32 v68, v36
	s_nop 0
	v_mul_f32_e32 v34, v34, v68
	v_pk_mul_f32 v[36:37], v[32:33], v[58:59]
	v_pk_mul_f32 v[68:69], v[34:35], v[34:35]
	v_pk_fma_f32 v[36:37], v[16:17], v[60:61], v[36:37]
	v_cvt_pk_bf16_f32 v34, v34, v35
	v_pk_fma_f32 v[36:37], v[20:21], v[64:65], v[36:37]
	s_nop 0
	v_pk_fma_f32 v[36:37], v[24:25], v[62:63], v[36:37]
	s_nop 0
	v_mul_f32_e32 v35, 0xbfb8aa3b, v36
	v_exp_f32_e32 v60, v35
	v_mul_f32_e32 v35, 0xbfb8aa3b, v37
	v_exp_f32_e32 v61, v35
	s_nop 0
	v_pk_add_f32 v[60:61], v[60:61], 1.0 op_sel_hi:[1,0]
	s_nop 0
	v_rcp_f32_e32 v75, v61
	s_nop 0
	v_mul_f32_e32 v37, v37, v75
	v_rcp_f32_e32 v61, v60
	s_nop 0
	v_mul_f32_e32 v36, v36, v61
	v_pk_mul_f32 v[60:61], v[36:37], v[36:37]
	v_cvt_pk_bf16_f32 v35, v36, v37
	v_pk_mul_f32 v[36:37], v[26:27], v[50:51]
	s_nop 0
	v_pk_fma_f32 v[36:37], v[2:3], v[52:53], v[36:37]
	s_nop 0
	v_pk_fma_f32 v[36:37], v[6:7], v[56:57], v[36:37]
	s_nop 0
	v_pk_fma_f32 v[36:37], v[10:11], v[54:55], v[36:37]
	s_nop 0
	v_mul_f32_e32 v52, 0xbfb8aa3b, v36
	v_mul_f32_e32 v53, 0xbfb8aa3b, v37
	v_exp_f32_e32 v52, v52
	v_exp_f32_e32 v53, v53
	s_nop 0
	v_pk_add_f32 v[52:53], v[52:53], 1.0 op_sel_hi:[1,0]
	s_nop 0
	v_rcp_f32_e32 v76, v53
	s_nop 0
	v_mul_f32_e32 v37, v37, v76
	v_div_scale_f32 v53, s[38:39], v52, v52, v36
	v_rcp_f32_e32 v75, v53
	s_nop 0
	v_fma_f32 v76, -v53, v75, 1.0
	v_fmac_f32_e32 v75, v76, v75
	v_div_scale_f32 v76, vcc, v36, v52, v36
	v_mul_f32_e32 v77, v76, v75
	v_fma_f32 v235, -v53, v77, v76
	v_fmac_f32_e32 v77, v235, v75
	v_fma_f32 v53, -v53, v77, v76
	v_div_fmas_f32 v53, v53, v75, v77
	v_pk_mul_f32 v[76:77], v[28:29], v[38:39]
	v_div_fixup_f32 v36, v53, v52, v36
	v_pk_fma_f32 v[40:41], v[4:5], v[40:41], v[76:77]
	v_pk_mul_f32 v[52:53], v[36:37], v[36:37]
	v_pk_fma_f32 v[40:41], v[8:9], v[44:45], v[40:41]
	v_cvt_pk_bf16_f32 v36, v36, v37
	v_pk_fma_f32 v[40:41], v[12:13], v[42:43], v[40:41]
	s_nop 0
	v_mul_f32_e32 v37, 0xbfb8aa3b, v40
	v_exp_f32_e32 v76, v37
	v_mul_f32_e32 v37, 0xbfb8aa3b, v41
	v_exp_f32_e32 v77, v37
	s_nop 0
	v_pk_add_f32 v[76:77], v[76:77], 1.0 op_sel_hi:[1,0]
	s_nop 0
	v_rcp_f32_e32 v75, v77
	s_nop 0
	v_mul_f32_e32 v41, v41, v75
	v_rcp_f32_e32 v75, v76
	s_nop 0
	v_mul_f32_e32 v40, v40, v75
	v_add_f32_e32 v37, v68, v69
	v_add_f32_e32 v37, v60, v37
	v_add_f32_e32 v37, v61, v37
	v_add_f32_e32 v37, v52, v37
	v_pk_mul_f32 v[76:77], v[40:41], v[40:41]
	v_add_f32_e32 v37, v53, v37
	v_add_f32_e32 v37, v76, v37
	v_add_f32_e32 v52, v77, v37
	v_cvt_pk_bf16_f32 v37, v40, v41
	v_lshlrev_b32_e32 v41, 8, v74
	v_add_f32_dpp v40, v52, v52 quad_perm:[1,0,3,2] row_mask:0xf bank_mask:0xf bound_ctrl:1
	s_nop 1
	v_add_f32_dpp v40, v40, v40 quad_perm:[2,3,0,1] row_mask:0xf bank_mask:0xf bound_ctrl:1
	s_nop 1
	v_add_f32_dpp v40, v40, v40 row_half_mirror row_mask:0xf bank_mask:0xf bound_ctrl:1
	s_nop 1
	v_add_f32_dpp v40, v40, v40 row_mirror row_mask:0xf bank_mask:0xf bound_ctrl:1
	s_and_saveexec_b64 s[38:39], s[10:11]
	s_xor_b64 s[38:39], exec, s[38:39]
	s_cbranch_execz .LBB0_309
	s_and_saveexec_b64 s[46:47], s[8:9]
	s_xor_b64 s[46:47], exec, s[46:47]
	v_add_u32_e32 v40, v232, v41
	ds_write_b128 v40, v[34:37] offset:33024
	s_andn2_saveexec_b64 s[46:47], s[46:47]
	s_cbranch_execz .LBB0_308
	v_lshlrev_b32_e32 v52, 4, v46
	v_xad_u32 v41, v52, s85, v41
	ds_write_b128 v41, v[34:37] offset:16640
	s_and_saveexec_b64 s[48:49], s[6:7]
	v_lshl_add_u32 v34, v74, 2, v224
	ds_write_b32 v34, v40
	s_or_b64 exec, exec, s[48:49]

; DI float siluf(float z) { return z / (1.f + __expf(-z)); }
; DI void phase_gdn_prep(const Params& p, int bid, int nb, char* smem) {
;     ...
; #pragma unroll
;       for (int i = 0; i < 16; i++) {
;         const int row = r0 + i;
;         float cur[8], o8[8];
;         unpack8(*(const u32x4*)(p.gqkv + (size_t)(t0 + row) * 1536 + gcol), cur);
;         float ss = 0.f;
; #pragma unroll
;         for (int e = 0; e < 8; e++) {
;           float v = cw[0][e] * w0[e] + cw[1][e] * w1[e] + cw[2][e] * w2[e] + cw[3][e] * cur[e];
;           v = siluf(v);
;           o8[e] = v; ss += v * v;
;           w0[e] = w1[e]; w1[e] = w2[e]; w2[e] = cur[e];
;         }
;         u32x4 pk = pack8(o8);
;         ss = sum16(ss);
;         if (tensor == 0) { *(u32x4*)(Qs + sw256(row, ch)) = pk; if (ch == 0) sSq[row] = ss; }
;         else if (tensor == 1) { *(u32x4*)(Ks + sw256(row, ch)) = pk; if (ch == 0) sSk[row] = ss; }
;         else { *(u32x4*)(Vs + row * 128 + ch * 8) = pk; }
;       }
.LBB0_313:
	s_or_b64 exec, exec, s[38:39]
	v_readlane_b32 s56, v253, 49
	v_or_b32_e32 v74, 10, v233
	v_readlane_b32 s62, v253, 55
	v_readlane_b32 s63, v253, 56
	v_add_u32_e32 v36, s77, v74
	v_readlane_b32 s57, v253, 50
	v_mov_b64_e32 v[34:35], s[62:63]
	v_mad_i64_i32 v[34:35], s[38:39], v36, s81, v[34:35]
	v_lshl_add_u64 v[34:35], v[48:49], 1, v[34:35]
	global_load_dwordx4 v[34:37], v[34:35], off
	v_readlane_b32 s58, v253, 51
	v_readlane_b32 s59, v253, 52
	v_readlane_b32 s60, v253, 53
	v_readlane_b32 s61, v253, 54
	v_readlane_b32 s64, v253, 57
	v_readlane_b32 s65, v253, 58
	v_readlane_b32 s66, v253, 59
	v_readlane_b32 s67, v253, 60
	v_readlane_b32 s68, v253, 61
	v_readlane_b32 s69, v253, 62
	v_readlane_b32 s70, v253, 63
	v_readlane_b32 s71, v252, 0
	s_waitcnt vmcnt(0)
	v_lshlrev_b32_e32 v68, 16, v34
	v_and_b32_e32 v69, 0xffff0000, v34
	v_lshlrev_b32_e32 v60, 16, v35
	v_and_b32_e32 v61, 0xffff0000, v35
	v_pk_mul_f32 v[34:35], v[30:31], v[72:73]
	v_lshlrev_b32_e32 v52, 16, v36
	v_pk_fma_f32 v[34:35], v[14:15], v[66:67], v[34:35]
	v_and_b32_e32 v53, 0xffff0000, v36
	v_pk_fma_f32 v[34:35], v[18:19], v[70:71], v[34:35]
	v_lshlrev_b32_e32 v40, 16, v37
	v_pk_fma_f32 v[34:35], v[22:23], v[68:69], v[34:35]
	v_and_b32_e32 v41, 0xffff0000, v37
	v_mul_f32_e32 v36, 0xbfb8aa3b, v34
	v_mul_f32_e32 v37, 0xbfb8aa3b, v35
	v_exp_f32_e32 v36, v36
	v_exp_f32_e32 v37, v37
	s_nop 0
	v_pk_add_f32 v[36:37], v[36:37], 1.0 op_sel_hi:[1,0]
	s_nop 0
	v_rcp_f32_e32 v67, v37
	s_nop 0
	v_mul_f32_e32 v35, v35, v67
	v_rcp_f32_e32 v66, v36
	s_nop 0
	v_mul_f32_e32 v34, v34, v66
	v_pk_mul_f32 v[36:37], v[32:33], v[64:65]
	v_pk_mul_f32 v[66:67], v[34:35], v[34:35]
	v_pk_fma_f32 v[36:37], v[16:17], v[58:59], v[36:37]
	v_cvt_pk_bf16_f32 v34, v34, v35
	v_pk_fma_f32 v[36:37], v[20:21], v[62:63], v[36:37]
	s_nop 0
	v_pk_fma_f32 v[36:37], v[24:25], v[60:61], v[36:37]
	s_nop 0
	v_mul_f32_e32 v35, 0xbfb8aa3b, v36
	v_exp_f32_e32 v58, v35
	v_mul_f32_e32 v35, 0xbfb8aa3b, v37
	v_exp_f32_e32 v59, v35
	s_nop 0
	v_pk_add_f32 v[58:59], v[58:59], 1.0 op_sel_hi:[1,0]
	s_nop 0
	v_rcp_f32_e32 v75, v59
	s_nop 0
	v_mul_f32_e32 v37, v37, v75
	v_rcp_f32_e32 v59, v58
	s_nop 0
	v_mul_f32_e32 v36, v36, v59
	v_pk_mul_f32 v[58:59], v[36:37], v[36:37]
	v_cvt_pk_bf16_f32 v35, v36, v37
	v_pk_mul_f32 v[36:37], v[26:27], v[56:57]
	s_nop 0
	v_pk_fma_f32 v[36:37], v[2:3], v[50:51], v[36:37]
	s_nop 0
	v_pk_fma_f32 v[36:37], v[6:7], v[54:55], v[36:37]
	s_nop 0
	v_pk_fma_f32 v[36:37], v[10:11], v[52:53], v[36:37]
	s_nop 0
	v_mul_f32_e32 v50, 0xbfb8aa3b, v36
	v_mul_f32_e32 v51, 0xbfb8aa3b, v37
	v_exp_f32_e32 v50, v50
	v_exp_f32_e32 v51, v51
	s_nop 0
	v_pk_add_f32 v[50:51], v[50:51], 1.0 op_sel_hi:[1,0]
	s_nop 0
	v_rcp_f32_e32 v76, v51
	s_nop 0
	v_mul_f32_e32 v37, v37, v76
	v_div_scale_f32 v51, s[38:39], v50, v50, v36
	v_rcp_f32_e32 v75, v51
	s_nop 0
	v_fma_f32 v76, -v51, v75, 1.0
	v_fmac_f32_e32 v75, v76, v75
	v_div_scale_f32 v76, vcc, v36, v50, v36
	v_mul_f32_e32 v77, v76, v75
	v_fma_f32 v235, -v51, v77, v76
	v_fmac_f32_e32 v77, v235, v75
	v_fma_f32 v51, -v51, v77, v76
	v_div_fmas_f32 v51, v51, v75, v77
	v_pk_mul_f32 v[76:77], v[28:29], v[44:45]
	v_div_fixup_f32 v36, v51, v50, v36
	v_pk_fma_f32 v[38:39], v[4:5], v[38:39], v[76:77]
	v_pk_mul_f32 v[50:51], v[36:37], v[36:37]
	v_pk_fma_f32 v[38:39], v[8:9], v[42:43], v[38:39]
	v_cvt_pk_bf16_f32 v36, v36, v37
	v_pk_fma_f32 v[38:39], v[12:13], v[40:41], v[38:39]
	s_nop 0
	v_mul_f32_e32 v37, 0xbfb8aa3b, v38
	v_exp_f32_e32 v76, v37
	v_mul_f32_e32 v37, 0xbfb8aa3b, v39
	v_exp_f32_e32 v77, v37
	s_nop 0
	v_pk_add_f32 v[76:77], v[76:77], 1.0 op_sel_hi:[1,0]
	s_nop 0
	v_rcp_f32_e32 v75, v77
	s_nop 0
	v_mul_f32_e32 v39, v39, v75
	v_rcp_f32_e32 v75, v76
	s_nop 0
	v_mul_f32_e32 v38, v38, v75
	v_add_f32_e32 v37, v66, v67
	v_add_f32_e32 v37, v58, v37
	v_add_f32_e32 v37, v59, v37
	v_add_f32_e32 v37, v50, v37
	v_pk_mul_f32 v[76:77], v[38:39], v[38:39]
	v_add_f32_e32 v37, v51, v37
	v_add_f32_e32 v37, v76, v37
	v_add_f32_e32 v50, v77, v37
	v_cvt_pk_bf16_f32 v37, v38, v39
	v_lshlrev_b32_e32 v39, 8, v74
	v_add_f32_dpp v38, v50, v50 quad_perm:[1,0,3,2] row_mask:0xf bank_mask:0xf bound_ctrl:1
	s_nop 1
	v_add_f32_dpp v38, v38, v38 quad_perm:[2,3,0,1] row_mask:0xf bank_mask:0xf bound_ctrl:1
	s_nop 1
	v_add_f32_dpp v38, v38, v38 row_half_mirror row_mask:0xf bank_mask:0xf bound_ctrl:1
	s_nop 1
	v_add_f32_dpp v38, v38, v38 row_mirror row_mask:0xf bank_mask:0xf bound_ctrl:1
	s_and_saveexec_b64 s[38:39], s[10:11]
	s_xor_b64 s[38:39], exec, s[38:39]
	s_cbranch_execz .LBB0_321
	s_and_saveexec_b64 s[46:47], s[8:9]
	s_xor_b64 s[46:47], exec, s[46:47]
	v_add_u32_e32 v38, v232, v39
	ds_write_b128 v38, v[34:37] offset:33024
	s_andn2_saveexec_b64 s[46:47], s[46:47]
	s_cbranch_execz .LBB0_320
	v_lshlrev_b32_e32 v50, 4, v46
	v_xad_u32 v39, v50, s86, v39
	ds_write_b128 v39, v[34:37] offset:16640
	s_and_saveexec_b64 s[48:49], s[6:7]
	v_lshl_add_u32 v34, v74, 2, v224
	ds_write_b32 v34, v38
	s_or_b64 exec, exec, s[48:49]

; DI float siluf(float z) { return z / (1.f + __expf(-z)); }
; DI void phase_gdn_prep(const Params& p, int bid, int nb, char* smem) {
;     ...
; #pragma unroll
;       for (int i = 0; i < 16; i++) {
;         const int row = r0 + i;
;         float cur[8], o8[8];
;         unpack8(*(const u32x4*)(p.gqkv + (size_t)(t0 + row) * 1536 + gcol), cur);
;         float ss = 0.f;
; #pragma unroll
;         for (int e = 0; e < 8; e++) {
;           float v = cw[0][e] * w0[e] + cw[1][e] * w1[e] + cw[2][e] * w2[e] + cw[3][e] * cur[e];
;           v = siluf(v);
;           o8[e] = v; ss += v * v;
;           w0[e] = w1[e]; w1[e] = w2[e]; w2[e] = cur[e];
;         }
;         u32x4 pk = pack8(o8);
;         ss = sum16(ss);
;         if (tensor == 0) { *(u32x4*)(Qs + sw256(row, ch)) = pk; if (ch == 0) sSq[row] = ss; }
;         else if (tensor == 1) { *(u32x4*)(Ks + sw256(row, ch)) = pk; if (ch == 0) sSk[row] = ss; }
;         else { *(u32x4*)(Vs + row * 128 + ch * 8) = pk; }
;       }
.LBB0_325:
	s_or_b64 exec, exec, s[38:39]
	v_readlane_b32 s56, v253, 49
	v_or_b32_e32 v74, 11, v233
	v_readlane_b32 s62, v253, 55
	v_readlane_b32 s63, v253, 56
	v_add_u32_e32 v36, s77, v74
	v_readlane_b32 s57, v253, 50
	v_mov_b64_e32 v[34:35], s[62:63]
	v_mad_i64_i32 v[34:35], s[38:39], v36, s81, v[34:35]
	v_lshl_add_u64 v[34:35], v[48:49], 1, v[34:35]
	global_load_dwordx4 v[34:37], v[34:35], off
	v_readlane_b32 s58, v253, 51
	v_readlane_b32 s59, v253, 52
	v_readlane_b32 s60, v253, 53
	v_readlane_b32 s61, v253, 54
	v_readlane_b32 s64, v253, 57
	v_readlane_b32 s65, v253, 58
	v_readlane_b32 s66, v253, 59
	v_readlane_b32 s67, v253, 60
	v_readlane_b32 s68, v253, 61
	v_readlane_b32 s69, v253, 62
	v_readlane_b32 s70, v253, 63
	v_readlane_b32 s71, v252, 0
	s_waitcnt vmcnt(0)
	v_lshlrev_b32_e32 v66, 16, v34
	v_and_b32_e32 v67, 0xffff0000, v34
	v_lshlrev_b32_e32 v58, 16, v35
	v_and_b32_e32 v59, 0xffff0000, v35
	v_pk_mul_f32 v[34:35], v[30:31], v[70:71]
	v_lshlrev_b32_e32 v50, 16, v36
	v_pk_fma_f32 v[34:35], v[14:15], v[72:73], v[34:35]
	v_and_b32_e32 v51, 0xffff0000, v36
	v_pk_fma_f32 v[34:35], v[18:19], v[68:69], v[34:35]
	v_lshlrev_b32_e32 v38, 16, v37
	v_pk_fma_f32 v[34:35], v[22:23], v[66:67], v[34:35]
	v_and_b32_e32 v39, 0xffff0000, v37
	v_mul_f32_e32 v36, 0xbfb8aa3b, v34
	v_mul_f32_e32 v37, 0xbfb8aa3b, v35
	v_exp_f32_e32 v36, v36
	v_exp_f32_e32 v37, v37
	s_nop 0
	v_pk_add_f32 v[36:37], v[36:37], 1.0 op_sel_hi:[1,0]
	s_nop 0
	v_rcp_f32_e32 v73, v37
	s_nop 0
	v_mul_f32_e32 v35, v35, v73
	v_rcp_f32_e32 v72, v36
	s_nop 0
	v_mul_f32_e32 v34, v34, v72
	v_pk_mul_f32 v[36:37], v[32:33], v[62:63]
	v_pk_mul_f32 v[72:73], v[34:35], v[34:35]
	v_pk_fma_f32 v[36:37], v[16:17], v[64:65], v[36:37]
	v_cvt_pk_bf16_f32 v34, v34, v35
	v_pk_fma_f32 v[36:37], v[20:21], v[60:61], v[36:37]
	s_nop 0
	v_pk_fma_f32 v[36:37], v[24:25], v[58:59], v[36:37]
	s_nop 0
	v_mul_f32_e32 v35, 0xbfb8aa3b, v36
	v_exp_f32_e32 v64, v35
	v_mul_f32_e32 v35, 0xbfb8aa3b, v37
	v_exp_f32_e32 v65, v35
	s_nop 0
	v_pk_add_f32 v[64:65], v[64:65], 1.0 op_sel_hi:[1,0]
	s_nop 0
	v_rcp_f32_e32 v75, v65
	s_nop 0
	v_mul_f32_e32 v37, v37, v75
	v_rcp_f32_e32 v65, v64
	s_nop 0
	v_mul_f32_e32 v36, v36, v65
	v_pk_mul_f32 v[64:65], v[36:37], v[36:37]
	v_cvt_pk_bf16_f32 v35, v36, v37
	v_pk_mul_f32 v[36:37], v[26:27], v[54:55]
	s_nop 0
	v_pk_fma_f32 v[36:37], v[2:3], v[56:57], v[36:37]
	s_nop 0
	v_pk_fma_f32 v[36:37], v[6:7], v[52:53], v[36:37]
	s_nop 0
	v_pk_fma_f32 v[36:37], v[10:11], v[50:51], v[36:37]
	s_nop 0
	v_mul_f32_e32 v56, 0xbfb8aa3b, v36
	v_mul_f32_e32 v57, 0xbfb8aa3b, v37
	v_exp_f32_e32 v56, v56
	v_exp_f32_e32 v57, v57
	s_nop 0
	v_pk_add_f32 v[56:57], v[56:57], 1.0 op_sel_hi:[1,0]
	s_nop 0
	v_rcp_f32_e32 v76, v57
	s_nop 0
	v_mul_f32_e32 v37, v37, v76
	v_div_scale_f32 v57, s[38:39], v56, v56, v36
	v_rcp_f32_e32 v75, v57
	s_nop 0
	v_fma_f32 v76, -v57, v75, 1.0
	v_fmac_f32_e32 v75, v76, v75
	v_div_scale_f32 v76, vcc, v36, v56, v36
	v_mul_f32_e32 v77, v76, v75
	v_fma_f32 v235, -v57, v77, v76
	v_fmac_f32_e32 v77, v235, v75
	v_fma_f32 v57, -v57, v77, v76
	v_div_fmas_f32 v57, v57, v75, v77
	v_pk_mul_f32 v[76:77], v[28:29], v[42:43]
	v_div_fixup_f32 v36, v57, v56, v36
	v_pk_fma_f32 v[44:45], v[4:5], v[44:45], v[76:77]
	v_pk_mul_f32 v[56:57], v[36:37], v[36:37]
	v_pk_fma_f32 v[44:45], v[8:9], v[40:41], v[44:45]
	v_cvt_pk_bf16_f32 v36, v36, v37
	v_pk_fma_f32 v[44:45], v[12:13], v[38:39], v[44:45]
	s_nop 0
	v_mul_f32_e32 v37, 0xbfb8aa3b, v44
	v_exp_f32_e32 v76, v37
	v_mul_f32_e32 v37, 0xbfb8aa3b, v45
	v_exp_f32_e32 v77, v37
	s_nop 0
	v_pk_add_f32 v[76:77], v[76:77], 1.0 op_sel_hi:[1,0]
	s_nop 0
	v_rcp_f32_e32 v75, v77
	s_nop 0
	v_mul_f32_e32 v45, v45, v75
	v_rcp_f32_e32 v75, v76
	s_nop 0
	v_mul_f32_e32 v44, v44, v75
	v_add_f32_e32 v37, v72, v73
	v_add_f32_e32 v37, v64, v37
	v_add_f32_e32 v37, v65, v37
	v_add_f32_e32 v37, v56, v37
	v_pk_mul_f32 v[76:77], v[44:45], v[44:45]
	v_add_f32_e32 v37, v57, v37
	v_add_f32_e32 v37, v76, v37
	v_add_f32_e32 v56, v77, v37
	v_cvt_pk_bf16_f32 v37, v44, v45
	v_lshlrev_b32_e32 v45, 8, v74
	v_add_f32_dpp v44, v56, v56 quad_perm:[1,0,3,2] row_mask:0xf bank_mask:0xf bound_ctrl:1
	s_nop 1
	v_add_f32_dpp v44, v44, v44 quad_perm:[2,3,0,1] row_mask:0xf bank_mask:0xf bound_ctrl:1
	s_nop 1
	v_add_f32_dpp v44, v44, v44 row_half_mirror row_mask:0xf bank_mask:0xf bound_ctrl:1
	s_nop 1
	v_add_f32_dpp v44, v44, v44 row_mirror row_mask:0xf bank_mask:0xf bound_ctrl:1
	s_and_saveexec_b64 s[38:39], s[10:11]
	s_xor_b64 s[38:39], exec, s[38:39]
	s_cbranch_execz .LBB0_333
	s_and_saveexec_b64 s[46:47], s[8:9]
	s_xor_b64 s[46:47], exec, s[46:47]
	v_add_u32_e32 v44, v232, v45
	ds_write_b128 v44, v[34:37] offset:33024
	s_andn2_saveexec_b64 s[46:47], s[46:47]
	s_cbranch_execz .LBB0_332
	v_lshlrev_b32_e32 v56, 4, v46
	v_xad_u32 v45, v56, s87, v45
	ds_write_b128 v45, v[34:37] offset:16640
	s_and_saveexec_b64 s[48:49], s[6:7]
	v_lshl_add_u32 v34, v74, 2, v224
	ds_write_b32 v34, v44
	s_or_b64 exec, exec, s[48:49]

; DI float siluf(float z) { return z / (1.f + __expf(-z)); }
; DI void phase_gdn_prep(const Params& p, int bid, int nb, char* smem) {
;     ...
; #pragma unroll
;       for (int i = 0; i < 16; i++) {
;         const int row = r0 + i;
;         float cur[8], o8[8];
;         unpack8(*(const u32x4*)(p.gqkv + (size_t)(t0 + row) * 1536 + gcol), cur);
;         float ss = 0.f;
; #pragma unroll
;         for (int e = 0; e < 8; e++) {
;           float v = cw[0][e] * w0[e] + cw[1][e] * w1[e] + cw[2][e] * w2[e] + cw[3][e] * cur[e];
;           v = siluf(v);
;           o8[e] = v; ss += v * v;
;           w0[e] = w1[e]; w1[e] = w2[e]; w2[e] = cur[e];
;         }
;         u32x4 pk = pack8(o8);
;         ss = sum16(ss);
;         if (tensor == 0) { *(u32x4*)(Qs + sw256(row, ch)) = pk; if (ch == 0) sSq[row] = ss; }
;         else if (tensor == 1) { *(u32x4*)(Ks + sw256(row, ch)) = pk; if (ch == 0) sSk[row] = ss; }
;         else { *(u32x4*)(Vs + row * 128 + ch * 8) = pk; }
;       }
.LBB0_337:
	s_or_b64 exec, exec, s[38:39]
	v_readlane_b32 s56, v253, 49
	v_or_b32_e32 v74, 12, v233
	v_readlane_b32 s62, v253, 55
	v_readlane_b32 s63, v253, 56
	v_add_u32_e32 v36, s77, v74
	v_readlane_b32 s57, v253, 50
	v_mov_b64_e32 v[34:35], s[62:63]
	v_mad_i64_i32 v[34:35], s[38:39], v36, s81, v[34:35]
	v_lshl_add_u64 v[34:35], v[48:49], 1, v[34:35]
	global_load_dwordx4 v[34:37], v[34:35], off
	v_readlane_b32 s58, v253, 51
	v_readlane_b32 s59, v253, 52
	v_readlane_b32 s60, v253, 53
	v_readlane_b32 s61, v253, 54
	v_readlane_b32 s64, v253, 57
	v_readlane_b32 s65, v253, 58
	v_readlane_b32 s66, v253, 59
	v_readlane_b32 s67, v253, 60
	v_readlane_b32 s68, v253, 61
	v_readlane_b32 s69, v253, 62
	v_readlane_b32 s70, v253, 63
	v_readlane_b32 s71, v252, 0
	s_waitcnt vmcnt(0)
	v_lshlrev_b32_e32 v72, 16, v34
	v_and_b32_e32 v73, 0xffff0000, v34
	v_lshlrev_b32_e32 v64, 16, v35
	v_and_b32_e32 v65, 0xffff0000, v35
	v_pk_mul_f32 v[34:35], v[30:31], v[68:69]
	v_lshlrev_b32_e32 v56, 16, v36
	v_pk_fma_f32 v[34:35], v[14:15], v[70:71], v[34:35]
	v_and_b32_e32 v57, 0xffff0000, v36
	v_pk_fma_f32 v[34:35], v[18:19], v[66:67], v[34:35]
	v_lshlrev_b32_e32 v44, 16, v37
	v_pk_fma_f32 v[34:35], v[22:23], v[72:73], v[34:35]
	v_and_b32_e32 v45, 0xffff0000, v37
	v_mul_f32_e32 v36, 0xbfb8aa3b, v34
	v_mul_f32_e32 v37, 0xbfb8aa3b, v35
	v_exp_f32_e32 v36, v36
	v_exp_f32_e32 v37, v37
	s_nop 0
	v_pk_add_f32 v[36:37], v[36:37], 1.0 op_sel_hi:[1,0]
	s_nop 0
	v_rcp_f32_e32 v71, v37
	s_nop 0
	v_mul_f32_e32 v35, v35, v71
	v_rcp_f32_e32 v70, v36
	s_nop 0
	v_mul_f32_e32 v34, v34, v70
	v_pk_mul_f32 v[36:37], v[32:33], v[60:61]
	v_pk_mul_f32 v[70:71], v[34:35], v[34:35]
	v_pk_fma_f32 v[36:37], v[16:17], v[62:63], v[36:37]
	v_cvt_pk_bf16_f32 v34, v34, v35
	v_pk_fma_f32 v[36:37], v[20:21], v[58:59], v[36:37]
	s_nop 0
	v_pk_fma_f32 v[36:37], v[24:25], v[64:65], v[36:37]
	s_nop 0
	v_mul_f32_e32 v35, 0xbfb8aa3b, v36
	v_exp_f32_e32 v62, v35
	v_mul_f32_e32 v35, 0xbfb8aa3b, v37
	v_exp_f32_e32 v63, v35
	s_nop 0
	v_pk_add_f32 v[62:63], v[62:63], 1.0 op_sel_hi:[1,0]
	s_nop 0
	v_rcp_f32_e32 v75, v63
	s_nop 0
	v_mul_f32_e32 v37, v37, v75
	v_rcp_f32_e32 v63, v62
	s_nop 0
	v_mul_f32_e32 v36, v36, v63
	v_pk_mul_f32 v[62:63], v[36:37], v[36:37]
	v_cvt_pk_bf16_f32 v35, v36, v37
	v_pk_mul_f32 v[36:37], v[26:27], v[52:53]
	s_nop 0
	v_pk_fma_f32 v[36:37], v[2:3], v[54:55], v[36:37]
	s_nop 0
	v_pk_fma_f32 v[36:37], v[6:7], v[50:51], v[36:37]
	s_nop 0
	v_pk_fma_f32 v[36:37], v[10:11], v[56:57], v[36:37]
	s_nop 0
	v_mul_f32_e32 v54, 0xbfb8aa3b, v36
	v_mul_f32_e32 v55, 0xbfb8aa3b, v37
	v_exp_f32_e32 v54, v54
	v_exp_f32_e32 v55, v55
	s_nop 0
	v_pk_add_f32 v[54:55], v[54:55], 1.0 op_sel_hi:[1,0]
	s_nop 0
	v_rcp_f32_e32 v76, v55
	s_nop 0
	v_mul_f32_e32 v37, v37, v76
	v_div_scale_f32 v55, s[38:39], v54, v54, v36
	v_rcp_f32_e32 v75, v55
	s_nop 0
	v_fma_f32 v76, -v55, v75, 1.0
	v_fmac_f32_e32 v75, v76, v75
	v_div_scale_f32 v76, vcc, v36, v54, v36
	v_mul_f32_e32 v77, v76, v75
	v_fma_f32 v235, -v55, v77, v76
	v_fmac_f32_e32 v77, v235, v75
	v_fma_f32 v55, -v55, v77, v76
	v_div_fmas_f32 v55, v55, v75, v77
	v_pk_mul_f32 v[76:77], v[28:29], v[40:41]
	v_div_fixup_f32 v36, v55, v54, v36
	v_pk_fma_f32 v[42:43], v[4:5], v[42:43], v[76:77]
	v_pk_mul_f32 v[54:55], v[36:37], v[36:37]
	v_pk_fma_f32 v[42:43], v[8:9], v[38:39], v[42:43]
	v_cvt_pk_bf16_f32 v36, v36, v37
	v_pk_fma_f32 v[42:43], v[12:13], v[44:45], v[42:43]
	s_nop 0
	v_mul_f32_e32 v37, 0xbfb8aa3b, v42
	v_exp_f32_e32 v76, v37
	v_mul_f32_e32 v37, 0xbfb8aa3b, v43
	v_exp_f32_e32 v77, v37
	s_nop 0
	v_pk_add_f32 v[76:77], v[76:77], 1.0 op_sel_hi:[1,0]
	s_nop 0
	v_rcp_f32_e32 v75, v77
	s_nop 0
	v_mul_f32_e32 v43, v43, v75
	v_rcp_f32_e32 v75, v76
	s_nop 0
	v_mul_f32_e32 v42, v42, v75
	v_add_f32_e32 v37, v70, v71
	v_add_f32_e32 v37, v62, v37
	v_add_f32_e32 v37, v63, v37
	v_add_f32_e32 v37, v54, v37
	v_pk_mul_f32 v[76:77], v[42:43], v[42:43]
	v_add_f32_e32 v37, v55, v37
	v_add_f32_e32 v37, v76, v37
	v_add_f32_e32 v54, v77, v37
	v_cvt_pk_bf16_f32 v37, v42, v43
	v_lshlrev_b32_e32 v43, 8, v74
	v_add_f32_dpp v42, v54, v54 quad_perm:[1,0,3,2] row_mask:0xf bank_mask:0xf bound_ctrl:1
	s_nop 1
	v_add_f32_dpp v42, v42, v42 quad_perm:[2,3,0,1] row_mask:0xf bank_mask:0xf bound_ctrl:1
	s_nop 1
	v_add_f32_dpp v42, v42, v42 row_half_mirror row_mask:0xf bank_mask:0xf bound_ctrl:1
	s_nop 1
	v_add_f32_dpp v42, v42, v42 row_mirror row_mask:0xf bank_mask:0xf bound_ctrl:1
	s_and_saveexec_b64 s[38:39], s[10:11]
	s_xor_b64 s[38:39], exec, s[38:39]
	s_cbranch_execz .LBB0_345
	s_and_saveexec_b64 s[46:47], s[8:9]
	s_xor_b64 s[46:47], exec, s[46:47]
	v_add_u32_e32 v42, v232, v43
	ds_write_b128 v42, v[34:37] offset:33024
	s_andn2_saveexec_b64 s[46:47], s[46:47]
	s_cbranch_execz .LBB0_344
	v_lshlrev_b32_e32 v54, 4, v46
	v_xad_u32 v43, v54, s80, v43
	ds_write_b128 v43, v[34:37] offset:16640
	s_and_saveexec_b64 s[48:49], s[6:7]
	v_lshl_add_u32 v34, v74, 2, v224
	ds_write_b32 v34, v42
	s_or_b64 exec, exec, s[48:49]

; DI float siluf(float z) { return z / (1.f + __expf(-z)); }
; DI void phase_gdn_prep(const Params& p, int bid, int nb, char* smem) {
;     ...
; #pragma unroll
;       for (int i = 0; i < 16; i++) {
;         const int row = r0 + i;
;         float cur[8], o8[8];
;         unpack8(*(const u32x4*)(p.gqkv + (size_t)(t0 + row) * 1536 + gcol), cur);
;         float ss = 0.f;
; #pragma unroll
;         for (int e = 0; e < 8; e++) {
;           float v = cw[0][e] * w0[e] + cw[1][e] * w1[e] + cw[2][e] * w2[e] + cw[3][e] * cur[e];
;           v = siluf(v);
;           o8[e] = v; ss += v * v;
;           w0[e] = w1[e]; w1[e] = w2[e]; w2[e] = cur[e];
;         }
;         u32x4 pk = pack8(o8);
;         ss = sum16(ss);
;         if (tensor == 0) { *(u32x4*)(Qs + sw256(row, ch)) = pk; if (ch == 0) sSq[row] = ss; }
;         else if (tensor == 1) { *(u32x4*)(Ks + sw256(row, ch)) = pk; if (ch == 0) sSk[row] = ss; }
;         else { *(u32x4*)(Vs + row * 128 + ch * 8) = pk; }
;       }
.LBB0_349:
	s_or_b64 exec, exec, s[38:39]
	v_readlane_b32 s56, v253, 49
	v_or_b32_e32 v74, 13, v233
	v_readlane_b32 s62, v253, 55
	v_readlane_b32 s63, v253, 56
	v_add_u32_e32 v36, s77, v74
	v_readlane_b32 s57, v253, 50
	v_mov_b64_e32 v[34:35], s[62:63]
	v_mad_i64_i32 v[34:35], s[38:39], v36, s81, v[34:35]
	v_lshl_add_u64 v[34:35], v[48:49], 1, v[34:35]
	global_load_dwordx4 v[34:37], v[34:35], off
	v_readlane_b32 s58, v253, 51
	v_readlane_b32 s59, v253, 52
	v_readlane_b32 s60, v253, 53
	v_readlane_b32 s61, v253, 54
	v_readlane_b32 s64, v253, 57
	v_readlane_b32 s65, v253, 58
	v_readlane_b32 s66, v253, 59
	v_readlane_b32 s67, v253, 60
	v_readlane_b32 s68, v253, 61
	v_readlane_b32 s69, v253, 62
	v_readlane_b32 s70, v253, 63
	v_readlane_b32 s71, v252, 0
	s_waitcnt vmcnt(0)
	v_lshlrev_b32_e32 v42, 16, v34
	v_and_b32_e32 v43, 0xffff0000, v34
	v_lshlrev_b32_e32 v54, 16, v35
	v_and_b32_e32 v55, 0xffff0000, v35
	v_pk_mul_f32 v[34:35], v[30:31], v[66:67]
	v_lshlrev_b32_e32 v62, 16, v36
	v_pk_fma_f32 v[34:35], v[14:15], v[68:69], v[34:35]
	v_and_b32_e32 v63, 0xffff0000, v36
	v_pk_fma_f32 v[34:35], v[18:19], v[72:73], v[34:35]
	v_lshlrev_b32_e32 v70, 16, v37
	v_pk_fma_f32 v[34:35], v[22:23], v[42:43], v[34:35]
	v_and_b32_e32 v71, 0xffff0000, v37
	v_mul_f32_e32 v36, 0xbfb8aa3b, v34
	v_mul_f32_e32 v37, 0xbfb8aa3b, v35
	v_exp_f32_e32 v36, v36
	v_exp_f32_e32 v37, v37
	s_nop 0
	v_pk_add_f32 v[36:37], v[36:37], 1.0 op_sel_hi:[1,0]
	s_nop 0
	v_rcp_f32_e32 v69, v37
	s_nop 0
	v_mul_f32_e32 v35, v35, v69
	v_rcp_f32_e32 v68, v36
	s_nop 0
	v_mul_f32_e32 v34, v34, v68
	v_pk_mul_f32 v[36:37], v[32:33], v[58:59]
	v_pk_mul_f32 v[68:69], v[34:35], v[34:35]
	v_pk_fma_f32 v[36:37], v[16:17], v[60:61], v[36:37]
	v_cvt_pk_bf16_f32 v34, v34, v35
	v_pk_fma_f32 v[36:37], v[20:21], v[64:65], v[36:37]
	s_nop 0
	v_pk_fma_f32 v[36:37], v[24:25], v[54:55], v[36:37]
	s_nop 0
	v_mul_f32_e32 v35, 0xbfb8aa3b, v36
	v_exp_f32_e32 v60, v35
	v_mul_f32_e32 v35, 0xbfb8aa3b, v37
	v_exp_f32_e32 v61, v35
	s_nop 0
	v_pk_add_f32 v[60:61], v[60:61], 1.0 op_sel_hi:[1,0]
	s_nop 0
	v_rcp_f32_e32 v75, v61
	s_nop 0
	v_mul_f32_e32 v37, v37, v75
	v_rcp_f32_e32 v61, v60
	s_nop 0
	v_mul_f32_e32 v36, v36, v61
	v_pk_mul_f32 v[60:61], v[36:37], v[36:37]
	v_cvt_pk_bf16_f32 v35, v36, v37
	v_pk_mul_f32 v[36:37], v[26:27], v[50:51]
	s_nop 0
	v_pk_fma_f32 v[36:37], v[2:3], v[52:53], v[36:37]
	s_nop 0
	v_pk_fma_f32 v[36:37], v[6:7], v[56:57], v[36:37]
	s_nop 0
	v_pk_fma_f32 v[36:37], v[10:11], v[62:63], v[36:37]
	s_nop 0
	v_mul_f32_e32 v52, 0xbfb8aa3b, v36
	v_mul_f32_e32 v53, 0xbfb8aa3b, v37
	v_exp_f32_e32 v52, v52
	v_exp_f32_e32 v53, v53
	s_nop 0
	v_pk_add_f32 v[52:53], v[52:53], 1.0 op_sel_hi:[1,0]
	s_nop 0
	v_rcp_f32_e32 v76, v53
	s_nop 0
	v_mul_f32_e32 v37, v37, v76
	v_div_scale_f32 v53, s[38:39], v52, v52, v36
	v_rcp_f32_e32 v75, v53
	s_nop 0
	v_fma_f32 v76, -v53, v75, 1.0
	v_fmac_f32_e32 v75, v76, v75
	v_div_scale_f32 v76, vcc, v36, v52, v36
	v_mul_f32_e32 v77, v76, v75
	v_fma_f32 v235, -v53, v77, v76
	v_fmac_f32_e32 v77, v235, v75
	v_fma_f32 v53, -v53, v77, v76
	v_div_fmas_f32 v53, v53, v75, v77
	v_pk_mul_f32 v[76:77], v[28:29], v[38:39]
	v_div_fixup_f32 v36, v53, v52, v36
	v_pk_fma_f32 v[40:41], v[4:5], v[40:41], v[76:77]
	v_pk_mul_f32 v[52:53], v[36:37], v[36:37]
	v_pk_fma_f32 v[40:41], v[8:9], v[44:45], v[40:41]
	v_cvt_pk_bf16_f32 v36, v36, v37
	v_pk_fma_f32 v[40:41], v[12:13], v[70:71], v[40:41]
	s_nop 0
	v_mul_f32_e32 v37, 0xbfb8aa3b, v40
	v_exp_f32_e32 v76, v37
	v_mul_f32_e32 v37, 0xbfb8aa3b, v41
	v_exp_f32_e32 v77, v37
	s_nop 0
	v_pk_add_f32 v[76:77], v[76:77], 1.0 op_sel_hi:[1,0]
	s_nop 0
	v_rcp_f32_e32 v75, v77
	s_nop 0
	v_mul_f32_e32 v41, v41, v75
	v_rcp_f32_e32 v75, v76
	s_nop 0
	v_mul_f32_e32 v40, v40, v75
	v_add_f32_e32 v37, v68, v69
	v_add_f32_e32 v37, v60, v37
	v_add_f32_e32 v37, v61, v37
	v_add_f32_e32 v37, v52, v37
	v_pk_mul_f32 v[76:77], v[40:41], v[40:41]
	v_add_f32_e32 v37, v53, v37
	v_add_f32_e32 v37, v76, v37
	v_add_f32_e32 v52, v77, v37
	v_cvt_pk_bf16_f32 v37, v40, v41
	v_lshlrev_b32_e32 v41, 8, v74
	v_add_f32_dpp v40, v52, v52 quad_perm:[1,0,3,2] row_mask:0xf bank_mask:0xf bound_ctrl:1
	s_nop 1
	v_add_f32_dpp v40, v40, v40 quad_perm:[2,3,0,1] row_mask:0xf bank_mask:0xf bound_ctrl:1
	s_nop 1
	v_add_f32_dpp v40, v40, v40 row_half_mirror row_mask:0xf bank_mask:0xf bound_ctrl:1
	s_nop 1
	v_add_f32_dpp v40, v40, v40 row_mirror row_mask:0xf bank_mask:0xf bound_ctrl:1
	s_and_saveexec_b64 s[38:39], s[10:11]
	s_xor_b64 s[38:39], exec, s[38:39]
	s_cbranch_execz .LBB0_357
	s_and_saveexec_b64 s[46:47], s[8:9]
	s_xor_b64 s[46:47], exec, s[46:47]
	v_add_u32_e32 v40, v232, v41
	ds_write_b128 v40, v[34:37] offset:33024
	s_andn2_saveexec_b64 s[46:47], s[46:47]
	s_cbranch_execz .LBB0_356
	v_lshlrev_b32_e32 v52, 4, v46
	s_movk_i32 s48, 0xd0
	v_xad_u32 v41, v52, s48, v41
	ds_write_b128 v41, v[34:37] offset:16640
	s_and_saveexec_b64 s[48:49], s[6:7]
	v_lshl_add_u32 v34, v74, 2, v224
	ds_write_b32 v34, v40
	s_or_b64 exec, exec, s[48:49]

; DI float siluf(float z) { return z / (1.f + __expf(-z)); }
; DI void phase_gdn_prep(const Params& p, int bid, int nb, char* smem) {
;     ...
; #pragma unroll
;       for (int i = 0; i < 16; i++) {
;         const int row = r0 + i;
;         float cur[8], o8[8];
;         unpack8(*(const u32x4*)(p.gqkv + (size_t)(t0 + row) * 1536 + gcol), cur);
;         float ss = 0.f;
; #pragma unroll
;         for (int e = 0; e < 8; e++) {
;           float v = cw[0][e] * w0[e] + cw[1][e] * w1[e] + cw[2][e] * w2[e] + cw[3][e] * cur[e];
;           v = siluf(v);
;           o8[e] = v; ss += v * v;
;           w0[e] = w1[e]; w1[e] = w2[e]; w2[e] = cur[e];
;         }
;         u32x4 pk = pack8(o8);
;         ss = sum16(ss);
;         if (tensor == 0) { *(u32x4*)(Qs + sw256(row, ch)) = pk; if (ch == 0) sSq[row] = ss; }
;         else if (tensor == 1) { *(u32x4*)(Ks + sw256(row, ch)) = pk; if (ch == 0) sSk[row] = ss; }
;         else { *(u32x4*)(Vs + row * 128 + ch * 8) = pk; }
;       }
.LBB0_361:
	s_or_b64 exec, exec, s[38:39]
	v_readlane_b32 s56, v253, 49
	v_or_b32_e32 v74, 14, v233
	v_readlane_b32 s62, v253, 55
	v_readlane_b32 s63, v253, 56
	v_add_u32_e32 v36, s77, v74
	v_readlane_b32 s57, v253, 50
	v_mov_b64_e32 v[34:35], s[62:63]
	v_mad_i64_i32 v[34:35], s[38:39], v36, s81, v[34:35]
	v_lshl_add_u64 v[34:35], v[48:49], 1, v[34:35]
	global_load_dwordx4 v[34:37], v[34:35], off
	v_readlane_b32 s58, v253, 51
	v_readlane_b32 s59, v253, 52
	v_readlane_b32 s60, v253, 53
	v_readlane_b32 s61, v253, 54
	v_readlane_b32 s64, v253, 57
	v_readlane_b32 s65, v253, 58
	v_readlane_b32 s66, v253, 59
	v_readlane_b32 s67, v253, 60
	v_readlane_b32 s68, v253, 61
	v_readlane_b32 s69, v253, 62
	v_readlane_b32 s70, v253, 63
	v_readlane_b32 s71, v252, 0
	s_waitcnt vmcnt(0)
	v_lshlrev_b32_e32 v68, 16, v34
	v_and_b32_e32 v69, 0xffff0000, v34
	v_lshlrev_b32_e32 v60, 16, v35
	v_and_b32_e32 v61, 0xffff0000, v35
	v_pk_mul_f32 v[34:35], v[30:31], v[72:73]
	v_lshlrev_b32_e32 v52, 16, v36
	v_pk_fma_f32 v[34:35], v[14:15], v[66:67], v[34:35]
	v_and_b32_e32 v53, 0xffff0000, v36
	v_pk_fma_f32 v[34:35], v[18:19], v[42:43], v[34:35]
	v_lshlrev_b32_e32 v40, 16, v37
	v_pk_fma_f32 v[34:35], v[22:23], v[68:69], v[34:35]
	v_and_b32_e32 v41, 0xffff0000, v37
	v_mul_f32_e32 v36, 0xbfb8aa3b, v34
	v_mul_f32_e32 v37, 0xbfb8aa3b, v35
	v_exp_f32_e32 v36, v36
	v_exp_f32_e32 v37, v37
	s_nop 0
	v_pk_add_f32 v[36:37], v[36:37], 1.0 op_sel_hi:[1,0]
	s_nop 0
	v_rcp_f32_e32 v67, v37
	s_nop 0
	v_mul_f32_e32 v35, v35, v67
	v_rcp_f32_e32 v66, v36
	s_nop 0
	v_mul_f32_e32 v34, v34, v66
	v_pk_mul_f32 v[36:37], v[32:33], v[64:65]
	v_pk_mul_f32 v[66:67], v[34:35], v[34:35]
	v_pk_fma_f32 v[36:37], v[16:17], v[58:59], v[36:37]
	v_cvt_pk_bf16_f32 v34, v34, v35
	v_pk_fma_f32 v[36:37], v[20:21], v[54:55], v[36:37]
	s_nop 0
	v_pk_fma_f32 v[36:37], v[24:25], v[60:61], v[36:37]
	s_nop 0
	v_mul_f32_e32 v35, 0xbfb8aa3b, v36
	v_exp_f32_e32 v58, v35
	v_mul_f32_e32 v35, 0xbfb8aa3b, v37
	v_exp_f32_e32 v59, v35
	s_nop 0
	v_pk_add_f32 v[58:59], v[58:59], 1.0 op_sel_hi:[1,0]
	s_nop 0
	v_rcp_f32_e32 v75, v59
	s_nop 0
	v_mul_f32_e32 v37, v37, v75
	v_rcp_f32_e32 v59, v58
	s_nop 0
	v_mul_f32_e32 v36, v36, v59
	v_pk_mul_f32 v[58:59], v[36:37], v[36:37]
	v_cvt_pk_bf16_f32 v35, v36, v37
	v_pk_mul_f32 v[36:37], v[26:27], v[56:57]
	s_nop 0
	v_pk_fma_f32 v[36:37], v[2:3], v[50:51], v[36:37]
	s_nop 0
	v_pk_fma_f32 v[36:37], v[6:7], v[62:63], v[36:37]
	s_nop 0
	v_pk_fma_f32 v[36:37], v[10:11], v[52:53], v[36:37]
	s_nop 0
	v_mul_f32_e32 v50, 0xbfb8aa3b, v36
	v_mul_f32_e32 v51, 0xbfb8aa3b, v37
	v_exp_f32_e32 v50, v50
	v_exp_f32_e32 v51, v51
	s_nop 0
	v_pk_add_f32 v[50:51], v[50:51], 1.0 op_sel_hi:[1,0]
	s_nop 0
	v_rcp_f32_e32 v76, v51
	s_nop 0
	v_mul_f32_e32 v37, v37, v76
	v_div_scale_f32 v51, s[38:39], v50, v50, v36
	v_rcp_f32_e32 v75, v51
	s_nop 0
	v_fma_f32 v76, -v51, v75, 1.0
	v_fmac_f32_e32 v75, v76, v75
	v_div_scale_f32 v76, vcc, v36, v50, v36
	v_mul_f32_e32 v77, v76, v75
	v_fma_f32 v235, -v51, v77, v76
	v_fmac_f32_e32 v77, v235, v75
	v_fma_f32 v51, -v51, v77, v76
	v_div_fmas_f32 v51, v51, v75, v77
	v_pk_mul_f32 v[76:77], v[28:29], v[44:45]
	v_div_fixup_f32 v36, v51, v50, v36
	v_pk_fma_f32 v[38:39], v[4:5], v[38:39], v[76:77]
	v_pk_mul_f32 v[50:51], v[36:37], v[36:37]
	v_pk_fma_f32 v[38:39], v[8:9], v[70:71], v[38:39]
	v_cvt_pk_bf16_f32 v36, v36, v37
	v_pk_fma_f32 v[38:39], v[12:13], v[40:41], v[38:39]
	s_nop 0
	v_mul_f32_e32 v37, 0xbfb8aa3b, v38
	v_exp_f32_e32 v76, v37
	v_mul_f32_e32 v37, 0xbfb8aa3b, v39
	v_exp_f32_e32 v77, v37
	s_nop 0
	v_pk_add_f32 v[76:77], v[76:77], 1.0 op_sel_hi:[1,0]
	s_nop 0
	v_rcp_f32_e32 v75, v77
	s_nop 0
	v_mul_f32_e32 v39, v39, v75
	v_rcp_f32_e32 v75, v76
	s_nop 0
	v_mul_f32_e32 v38, v38, v75
	v_add_f32_e32 v37, v66, v67
	v_add_f32_e32 v37, v58, v37
	v_add_f32_e32 v37, v59, v37
	v_add_f32_e32 v37, v50, v37
	v_pk_mul_f32 v[76:77], v[38:39], v[38:39]
	v_add_f32_e32 v37, v51, v37
	v_add_f32_e32 v37, v76, v37
	v_add_f32_e32 v50, v77, v37
	v_cvt_pk_bf16_f32 v37, v38, v39
	v_lshlrev_b32_e32 v39, 8, v74
	v_add_f32_dpp v38, v50, v50 quad_perm:[1,0,3,2] row_mask:0xf bank_mask:0xf bound_ctrl:1
	s_nop 1
	v_add_f32_dpp v38, v38, v38 quad_perm:[2,3,0,1] row_mask:0xf bank_mask:0xf bound_ctrl:1
	s_nop 1
	v_add_f32_dpp v38, v38, v38 row_half_mirror row_mask:0xf bank_mask:0xf bound_ctrl:1
	s_nop 1
	v_add_f32_dpp v38, v38, v38 row_mirror row_mask:0xf bank_mask:0xf bound_ctrl:1
	s_and_saveexec_b64 s[38:39], s[10:11]
	s_xor_b64 s[38:39], exec, s[38:39]
	s_cbranch_execz .LBB0_369
	s_and_saveexec_b64 s[46:47], s[8:9]
	s_xor_b64 s[46:47], exec, s[46:47]
	v_add_u32_e32 v38, v232, v39
	ds_write_b128 v38, v[34:37] offset:33024
	s_andn2_saveexec_b64 s[46:47], s[46:47]
	s_cbranch_execz .LBB0_368
	v_lshlrev_b32_e32 v50, 4, v46
	s_movk_i32 s48, 0xe0
	v_xad_u32 v39, v50, s48, v39
	ds_write_b128 v39, v[34:37] offset:16640
	s_and_saveexec_b64 s[48:49], s[6:7]
	v_lshl_add_u32 v34, v74, 2, v224
	ds_write_b32 v34, v38
	s_or_b64 exec, exec, s[48:49]

; DI float siluf(float z) { return z / (1.f + __expf(-z)); }
; DI void phase_gdn_prep(const Params& p, int bid, int nb, char* smem) {
;     ...
;       for (int i = 0; i < 16; i++) {
;         const int row = r0 + i;
;         float cur[8], o8[8];
;         unpack8(*(const u32x4*)(p.gqkv + (size_t)(t0 + row) * 1536 + gcol), cur);
;         float ss = 0.f;
; #pragma unroll
;         for (int e = 0; e < 8; e++) {
;           float v = cw[0][e] * w0[e] + cw[1][e] * w1[e] + cw[2][e] * w2[e] + cw[3][e] * cur[e];
;           v = siluf(v);
;           o8[e] = v; ss += v * v;
;           w0[e] = w1[e]; w1[e] = w2[e]; w2[e] = cur[e];
;         }
;         u32x4 pk = pack8(o8);
;         ss = sum16(ss);
;         if (tensor == 0) { *(u32x4*)(Qs + sw256(row, ch)) = pk; if (ch == 0) sSq[row] = ss; }
;         else if (tensor == 1) { *(u32x4*)(Ks + sw256(row, ch)) = pk; if (ch == 0) sSk[row] = ss; }
;         else { *(u32x4*)(Vs + row * 128 + ch * 8) = pk; }
.LBB0_373:
	s_or_b64 exec, exec, s[38:39]
	v_readlane_b32 s56, v253, 49
	v_or_b32_e32 v38, 15, v233
	v_readlane_b32 s62, v253, 55
	v_readlane_b32 s63, v253, 56
	v_add_u32_e32 v36, s77, v38
	v_pk_mul_f32 v[42:43], v[30:31], v[42:43]
	v_mov_b64_e32 v[34:35], s[62:63]
	v_mad_i64_i32 v[34:35], s[38:39], v36, s81, v[34:35]
	v_lshl_add_u64 v[34:35], v[48:49], 1, v[34:35]
	global_load_dwordx4 v[34:37], v[34:35], off
	v_pk_fma_f32 v[14:15], v[14:15], v[72:73], v[42:43]
	v_pk_mul_f32 v[30:31], v[26:27], v[62:63]
	v_pk_mul_f32 v[26:27], v[28:29], v[70:71]
	v_pk_fma_f32 v[14:15], v[18:19], v[68:69], v[14:15]
	v_pk_mul_f32 v[32:33], v[32:33], v[54:55]
	v_pk_fma_f32 v[2:3], v[2:3], v[56:57], v[30:31]
	v_pk_fma_f32 v[16:17], v[16:17], v[64:65], v[32:33]
	v_pk_fma_f32 v[2:3], v[6:7], v[52:53], v[2:3]
	v_pk_fma_f32 v[16:17], v[20:21], v[60:61], v[16:17]
	v_pk_fma_f32 v[4:5], v[4:5], v[44:45], v[26:27]
	v_readlane_b32 s57, v253, 50
	v_pk_fma_f32 v[4:5], v[8:9], v[40:41], v[4:5]
	v_readlane_b32 s58, v253, 51
	v_readlane_b32 s59, v253, 52
	v_readlane_b32 s60, v253, 53
	v_readlane_b32 s61, v253, 54
	v_readlane_b32 s64, v253, 57
	v_readlane_b32 s65, v253, 58
	v_readlane_b32 s66, v253, 59
	v_readlane_b32 s67, v253, 60
	v_readlane_b32 s68, v253, 61
	v_readlane_b32 s69, v253, 62
	v_readlane_b32 s70, v253, 63
	v_readlane_b32 s71, v252, 0
	s_waitcnt vmcnt(0)
	v_lshlrev_b32_e32 v28, 16, v34
	v_and_b32_e32 v29, 0xffff0000, v34
	v_pk_fma_f32 v[14:15], v[22:23], v[28:29], v[14:15]
	s_nop 0
	v_mul_f32_e32 v18, 0xbfb8aa3b, v14
	v_mul_f32_e32 v19, 0xbfb8aa3b, v15
	v_exp_f32_e32 v18, v18
	v_exp_f32_e32 v19, v19
	s_nop 0
	v_pk_add_f32 v[18:19], v[18:19], 1.0 op_sel_hi:[1,0]
	s_nop 0
	v_rcp_f32_e32 v23, v19
	s_nop 0
	v_mul_f32_e32 v15, v15, v23
	v_div_scale_f32 v19, s[38:39], v18, v18, v14
	v_rcp_f32_e32 v22, v19
	s_nop 0
	v_fma_f32 v23, -v19, v22, 1.0
	v_fmac_f32_e32 v22, v23, v22
	v_div_scale_f32 v23, vcc, v14, v18, v14
	v_mul_f32_e32 v28, v23, v22
	v_fma_f32 v29, -v19, v28, v23
	v_fmac_f32_e32 v28, v29, v22
	v_fma_f32 v19, -v19, v28, v23
	v_div_fmas_f32 v19, v19, v22, v28
	v_lshlrev_b32_e32 v22, 16, v35
	v_and_b32_e32 v23, 0xffff0000, v35
	v_div_fixup_f32 v14, v19, v18, v14
	v_pk_fma_f32 v[16:17], v[24:25], v[22:23], v[16:17]
	v_pk_mul_f32 v[18:19], v[14:15], v[14:15]
	v_cvt_pk_bf16_f32 v14, v14, v15
	v_mul_f32_e32 v15, 0xbfb8aa3b, v16
	v_exp_f32_e32 v20, v15
	v_mul_f32_e32 v15, 0xbfb8aa3b, v17
	v_exp_f32_e32 v21, v15
	s_nop 0
	v_pk_add_f32 v[20:21], v[20:21], 1.0 op_sel_hi:[1,0]
	s_nop 0
	v_rcp_f32_e32 v22, v21
	s_nop 0
	v_mul_f32_e32 v17, v17, v22
	v_rcp_f32_e32 v21, v20
	s_nop 0
	v_mul_f32_e32 v16, v16, v21
	v_pk_mul_f32 v[20:21], v[16:17], v[16:17]
	v_cvt_pk_bf16_f32 v15, v16, v17
	v_lshlrev_b32_e32 v16, 16, v36
	v_and_b32_e32 v17, 0xffff0000, v36
	v_pk_fma_f32 v[2:3], v[10:11], v[16:17], v[2:3]
	s_nop 0
	v_mul_f32_e32 v6, 0xbfb8aa3b, v2
	v_mul_f32_e32 v7, 0xbfb8aa3b, v3
	v_exp_f32_e32 v6, v6
	v_exp_f32_e32 v7, v7
	s_nop 0
	v_pk_add_f32 v[6:7], v[6:7], 1.0 op_sel_hi:[1,0]
	s_nop 0
	v_rcp_f32_e32 v11, v7
	s_nop 0
	v_mul_f32_e32 v3, v3, v11
	v_rcp_f32_e32 v10, v6
	s_nop 0
	v_mul_f32_e32 v2, v2, v10
	v_pk_mul_f32 v[6:7], v[2:3], v[2:3]
	v_cvt_pk_bf16_f32 v16, v2, v3
	v_lshlrev_b32_e32 v2, 16, v37
	v_and_b32_e32 v3, 0xffff0000, v37
	v_pk_fma_f32 v[2:3], v[12:13], v[2:3], v[4:5]
	s_nop 0
	v_mul_f32_e32 v4, 0xbfb8aa3b, v2
	v_mul_f32_e32 v5, 0xbfb8aa3b, v3
	v_exp_f32_e32 v4, v4
	v_exp_f32_e32 v5, v5
	s_nop 0
	v_pk_add_f32 v[4:5], v[4:5], 1.0 op_sel_hi:[1,0]
	s_nop 0
	v_rcp_f32_e32 v9, v5
	s_nop 0
	v_mul_f32_e32 v3, v3, v9
	v_div_scale_f32 v5, s[38:39], v4, v4, v2
	v_rcp_f32_e32 v8, v5
	s_nop 0
	v_fma_f32 v9, -v5, v8, 1.0
	v_fmac_f32_e32 v8, v9, v8
	v_div_scale_f32 v9, vcc, v2, v4, v2
	v_mul_f32_e32 v10, v9, v8
	v_fma_f32 v11, -v5, v10, v9
	v_fmac_f32_e32 v10, v11, v8
	v_fma_f32 v5, -v5, v10, v9
	v_div_fmas_f32 v5, v5, v8, v10
	v_add_f32_e32 v8, v18, v19
	v_add_f32_e32 v8, v20, v8
	v_add_f32_e32 v8, v21, v8
	v_div_fixup_f32 v2, v5, v4, v2
	v_add_f32_e32 v6, v6, v8
	v_pk_mul_f32 v[4:5], v[2:3], v[2:3]
	v_add_f32_e32 v6, v7, v6
	v_add_f32_e32 v4, v4, v6
	v_add_f32_e32 v4, v5, v4
	v_cvt_pk_bf16_f32 v17, v2, v3
	v_lshlrev_b32_e32 v3, 8, v38
	v_add_f32_dpp v2, v4, v4 quad_perm:[1,0,3,2] row_mask:0xf bank_mask:0xf bound_ctrl:1
	s_nop 1
	v_add_f32_dpp v2, v2, v2 quad_perm:[2,3,0,1] row_mask:0xf bank_mask:0xf bound_ctrl:1
	s_nop 1
	v_add_f32_dpp v2, v2, v2 row_half_mirror row_mask:0xf bank_mask:0xf bound_ctrl:1
	s_nop 1
	v_add_f32_dpp v2, v2, v2 row_mirror row_mask:0xf bank_mask:0xf bound_ctrl:1
	s_and_saveexec_b64 s[38:39], s[10:11]
	s_xor_b64 s[10:11], exec, s[38:39]
	s_cbranch_execz .LBB0_381
	s_and_saveexec_b64 s[38:39], s[8:9]
	s_xor_b64 s[8:9], exec, s[38:39]
	v_add_u32_e32 v2, v232, v3
	ds_write_b128 v2, v[14:17] offset:33024
	s_andn2_saveexec_b64 s[8:9], s[8:9]
	s_cbranch_execz .LBB0_380
	v_lshlrev_b32_e32 v4, 4, v46
	v_xad_u32 v3, v4, s33, v3
	ds_write_b128 v3, v[14:17] offset:16640
	s_and_saveexec_b64 s[38:39], s[6:7]
	v_lshl_add_u32 v3, v38, 2, v224
	ds_write_b32 v3, v2
	s_or_b64 exec, exec, s[38:39]
